# previous combined version plus attention q-norm gain loads hoisted and issued together (one wait instead of four per head)
# baseline (speedup 1.0000x reference)
; __device__ __forceinline__ unsigned pk2(float lo, float hi) { const f32x2 v = {lo, hi}; return __builtin_bit_cast(unsigned, __builtin_convertvector(v, bf16x2_t)); }
; __device__ __forceinline__ void unpack8(u32x4 w, float* f) { f[0] = bflo(w.x); f[1] = bfhi(w.x); f[2] = bflo(w.y); f[3] = bfhi(w.y); f[4] = bflo(w.z); f[5] = bfhi(w.z); f[6] = bflo(w.w); f[7] = bfhi(w.w); }
; __device__ __forceinline__ void attn_phase(CArgs a, int l, LAS unsigned char* lds, int tid, int lane, int wave, int G, int bx) {
;     ...
;                 for (int st = 0; st < 4; ++st) unpack8(qraw[st], qv[st]);
;                 if (hh == 0) {
; #pragma unroll
;                     for (int st = 0; st < 4; ++st) qraw[st] = *(const u32x4*)(PROJ + (size_t)qtok * NPJ + (h + 1) * 64 + st * 16 + hf * 8); }
; #pragma unroll
;                 for (int st = 0; st < 4; ++st) {
; #pragma unroll
;                     for (int j = 0; j < 8; ++j) ss += qv[st][j] * qv[st][j]; }
;                 ss += __shfl_xor(ss, 32);
;                 const float rs = rsqrtf(ss * (1.0f / 64.0f) + EPS) * 0.125f;
; #pragma unroll
;                 for (int st = 0; st < 4; ++st) { const float* qg = a->in[22] + ll * 64 + st * 16 + hf * 8; u32x4 w;
;                     w.x = pk2(qv[st][0] * rs * qg[0], qv[st][1] * rs * qg[1]); w.y = pk2(qv[st][2] * rs * qg[2], qv[st][3] * rs * qg[3]);
;                     w.z = pk2(qv[st][4] * rs * qg[4], qv[st][5] * rs * qg[5]); w.w = pk2(qv[st][6] * rs * qg[6], qv[st][7] * rs * qg[7]);
;                     qf[st] = __builtin_bit_cast(bf16x8, w); } }
;             const float sink = a->in[24][ll * 16 + h]; float mx = sink, sum = 0.f;
.LBB0_359:
	v_lshlrev_b32_e32 v16, 16, v12
	v_and_b32_e32 v17, 0xffff0000, v12
	v_lshlrev_b32_e32 v12, 16, v13
	v_and_b32_e32 v13, 0xffff0000, v13
	v_lshlrev_b32_e32 v32, 16, v0
	v_and_b32_e32 v33, 0xffff0000, v0
	v_lshlrev_b32_e32 v34, 16, v1
	v_and_b32_e32 v35, 0xffff0000, v1
	v_pk_mul_f32 v[0:1], v[16:17], v[16:17]
	v_lshlrev_b32_e32 v36, 16, v2
	v_and_b32_e32 v37, 0xffff0000, v2
	v_lshlrev_b32_e32 v38, 16, v3
	v_and_b32_e32 v39, 0xffff0000, v3
	v_pk_mul_f32 v[2:3], v[12:13], v[12:13]
	v_add_f32_e32 v0, v0, v1
	v_lshlrev_b32_e32 v18, 16, v14
	v_and_b32_e32 v19, 0xffff0000, v14
	v_add_f32_e32 v0, v2, v0
	v_lshlrev_b32_e32 v24, 16, v4
	v_and_b32_e32 v25, 0xffff0000, v4
	v_lshlrev_b32_e32 v26, 16, v5
	v_and_b32_e32 v27, 0xffff0000, v5
	v_pk_mul_f32 v[4:5], v[18:19], v[18:19]
	v_add_f32_e32 v0, v3, v0
	v_lshlrev_b32_e32 v14, 16, v15
	v_and_b32_e32 v15, 0xffff0000, v15
	v_add_f32_e32 v0, v4, v0
	v_lshlrev_b32_e32 v28, 16, v6
	v_and_b32_e32 v29, 0xffff0000, v6
	v_lshlrev_b32_e32 v30, 16, v7
	v_and_b32_e32 v31, 0xffff0000, v7
	v_pk_mul_f32 v[6:7], v[14:15], v[14:15]
	v_add_f32_e32 v0, v5, v0
	v_lshlrev_b32_e32 v20, 16, v8
	v_and_b32_e32 v21, 0xffff0000, v8
	v_add_f32_e32 v0, v6, v0
	v_pk_mul_f32 v[40:41], v[20:21], v[20:21]
	v_add_f32_e32 v0, v7, v0
	v_lshlrev_b32_e32 v8, 16, v9
	v_and_b32_e32 v9, 0xffff0000, v9
	v_add_f32_e32 v0, v40, v0
	v_pk_mul_f32 v[42:43], v[8:9], v[8:9]
	v_add_f32_e32 v0, v41, v0
	v_lshlrev_b32_e32 v22, 16, v10
	v_and_b32_e32 v23, 0xffff0000, v10
	v_add_f32_e32 v0, v42, v0
	v_pk_mul_f32 v[44:45], v[22:23], v[22:23]
	v_add_f32_e32 v0, v43, v0
	v_lshlrev_b32_e32 v10, 16, v11
	v_and_b32_e32 v11, 0xffff0000, v11
	v_add_f32_e32 v0, v44, v0
	v_pk_mul_f32 v[46:47], v[10:11], v[10:11]
	v_add_f32_e32 v0, v45, v0
	v_add_f32_e32 v0, v46, v0
	v_pk_mul_f32 v[48:49], v[24:25], v[24:25]
	v_add_f32_e32 v0, v47, v0
	v_add_f32_e32 v0, v48, v0
	v_pk_mul_f32 v[50:51], v[26:27], v[26:27]
	v_add_f32_e32 v0, v49, v0
	v_add_f32_e32 v0, v50, v0
	v_pk_mul_f32 v[52:53], v[28:29], v[28:29]
	v_add_f32_e32 v0, v51, v0
	v_add_f32_e32 v0, v52, v0
	v_pk_mul_f32 v[54:55], v[30:31], v[30:31]
	v_add_f32_e32 v0, v53, v0
	v_add_f32_e32 v0, v54, v0
	v_pk_mul_f32 v[56:57], v[32:33], v[32:33]
	v_add_f32_e32 v0, v55, v0
	v_add_f32_e32 v0, v56, v0
	v_pk_mul_f32 v[58:59], v[34:35], v[34:35]
	v_add_f32_e32 v0, v57, v0
	v_add_f32_e32 v0, v58, v0
	v_pk_mul_f32 v[60:61], v[36:37], v[36:37]
	v_add_f32_e32 v0, v59, v0
	v_add_f32_e32 v0, v60, v0
	v_pk_mul_f32 v[62:63], v[38:39], v[38:39]
	v_add_f32_e32 v0, v61, v0
	v_add_f32_e32 v0, v62, v0
	v_add_f32_e32 v0, v63, v0
	ds_bpermute_b32 v1, v171, v0
	v_readlane_b32 s2, v255, 29
	s_or_b32 s2, s90, s2
	s_add_i32 s90, s2, s33
	v_lshl_add_u32 v229, s2, 10, v227
	s_waitcnt lgkmcnt(0)
	v_add_f32_e32 v0, v0, v1
	v_fmamk_f32 v0, v0, 0x3c800000, v162
	v_cmp_gt_f32_e32 vcc, s91, v0
	v_mul_f32_e32 v1, 0x4b800000, v0
	s_ashr_i32 s91, s90, 31
	v_cndmask_b32_e32 v0, v0, v1, vcc
	v_rsq_f32_e32 v0, v0
	s_lshl_b64 s[90:91], s[90:91], 2
	s_add_u32 s90, s86, s90
	s_addc_u32 s91, s87, s91
	v_mul_f32_e32 v1, 0x45800000, v0
	v_cndmask_b32_e32 v0, v0, v1, vcc
	v_mul_f32_e32 v40, 0x3e000000, v0
	global_load_dwordx4 v[0:3], v[174:175], off offset:16
	global_load_dwordx4 v[4:7], v[174:175], off
	global_load_dwordx4 v[74:77], v[174:175], off offset:80
	global_load_dwordx4 v[78:81], v[174:175], off offset:64
	global_load_dwordx4 v[82:85], v[174:175], off offset:144
	global_load_dwordx4 v[86:89], v[174:175], off offset:128
	global_load_dwordx4 v[90:93], v[174:175], off offset:208
	global_load_dwordx4 v[94:97], v[174:175], off offset:192
	v_pk_mul_f32 v[16:17], v[40:41], v[16:17] op_sel_hi:[0,1]
	v_add_u32_e32 v230, 0x3000, v153
	s_waitcnt vmcnt(0)
	v_pk_mul_f32 v[4:5], v[4:5], v[16:17]
	s_nop 0
	v_cvt_pk_bf16_f32 v138, v4, v5
	v_pk_mul_f32 v[4:5], v[40:41], v[12:13] op_sel_hi:[0,1]
	v_pk_mul_f32 v[4:5], v[6:7], v[4:5]
	v_pk_mul_f32 v[12:13], v[40:41], v[20:21] op_sel_hi:[0,1]
	v_cvt_pk_bf16_f32 v139, v4, v5
	v_pk_mul_f32 v[4:5], v[40:41], v[18:19] op_sel_hi:[0,1]
	v_pk_mul_f32 v[0:1], v[0:1], v[4:5]
	s_nop 0
	v_cvt_pk_bf16_f32 v140, v0, v1
	v_pk_mul_f32 v[0:1], v[40:41], v[14:15] op_sel_hi:[0,1]
	v_pk_mul_f32 v[0:1], v[2:3], v[0:1]
	s_nop 0
	v_cvt_pk_bf16_f32 v141, v0, v1
	s_waitcnt vmcnt(0)
	v_pk_mul_f32 v[4:5], v[78:79], v[12:13]
	s_nop 0
	v_cvt_pk_bf16_f32 v142, v4, v5
	v_pk_mul_f32 v[4:5], v[40:41], v[8:9] op_sel_hi:[0,1]
	v_pk_mul_f32 v[4:5], v[4:5], v[80:81]
	v_pk_mul_f32 v[8:9], v[40:41], v[24:25] op_sel_hi:[0,1]
	v_cvt_pk_bf16_f32 v143, v4, v5
	v_pk_mul_f32 v[4:5], v[40:41], v[22:23] op_sel_hi:[0,1]
	v_pk_mul_f32 v[0:1], v[4:5], v[74:75]
	s_nop 0
	v_cvt_pk_bf16_f32 v144, v0, v1
	v_pk_mul_f32 v[0:1], v[40:41], v[10:11] op_sel_hi:[0,1]
	v_pk_mul_f32 v[0:1], v[0:1], v[76:77]
	s_nop 0
	v_cvt_pk_bf16_f32 v145, v0, v1
	s_waitcnt vmcnt(0)
	v_pk_mul_f32 v[4:5], v[8:9], v[86:87]
	s_nop 0
	v_cvt_pk_bf16_f32 v134, v4, v5
	v_pk_mul_f32 v[4:5], v[40:41], v[26:27] op_sel_hi:[0,1]
	v_pk_mul_f32 v[4:5], v[4:5], v[88:89]
	v_pk_mul_f32 v[8:9], v[40:41], v[32:33] op_sel_hi:[0,1]
	v_cvt_pk_bf16_f32 v135, v4, v5
	v_pk_mul_f32 v[4:5], v[40:41], v[28:29] op_sel_hi:[0,1]
	v_pk_mul_f32 v[0:1], v[4:5], v[82:83]
	s_nop 0
	v_cvt_pk_bf16_f32 v136, v0, v1
	v_pk_mul_f32 v[0:1], v[40:41], v[30:31] op_sel_hi:[0,1]
	v_pk_mul_f32 v[0:1], v[0:1], v[84:85]
	s_nop 0
	v_cvt_pk_bf16_f32 v137, v0, v1
	global_load_dword v228, v161, s[90:91]
	v_readlane_b32 s90, v255, 3
	v_readlane_b32 s91, v255, 4
	s_waitcnt vmcnt(1)
; #define LAS __attribute__((address_space(3)))
; __device__ __forceinline__ int crow(int r, int h) { return (r & 3) + 8 * (r >> 2) + 4 * h; }
; __device__ __forceinline__ void attn_phase(CArgs a, int l, LAS unsigned char* lds, int tid, int lane, int wave, int G, int bx) {
;     ...
;                 for (int st = 0; st < 4; ++st) { const float* qg = a->in[22] + ll * 64 + st * 16 + hf * 8; u32x4 w;
;                     w.x = pk2(qv[st][0] * rs * qg[0], qv[st][1] * rs * qg[1]); w.y = pk2(qv[st][2] * rs * qg[2], qv[st][3] * rs * qg[3]);
;                     w.z = pk2(qv[st][4] * rs * qg[4], qv[st][5] * rs * qg[5]); w.w = pk2(qv[st][6] * rs * qg[6], qv[st][7] * rs * qg[7]);
;                     qf[st] = __builtin_bit_cast(bf16x8, w); } }
;             const float sink = a->in[24][ll * 16 + h]; float mx = sink, sum = 0.f;
;             const LAS float* blh = BL + h * 256 + 63 - qi;
;             f32x16 o0, o1;
; #pragma unroll
;             for (int i = 0; i < 16; ++i) { o0[i] = 0.f; o1[i] = 0.f; }
; #pragma unroll
;             for (int ps = 0; ps < 6; ++ps) {
;                 asm volatile("" ::: "memory");
;                 float sv[1][16];
; #pragma unroll
;                 for (int t3 = 0; t3 < 1; ++t3) { const int tt = ps + t3; f32x16 sa;
; #pragma unroll
;                     for (int i = 0; i < 16; ++i) sa[i] = 0.f;
; #pragma unroll
;                     for (int st = 0; st < 4; ++st) { const bf16x8 kf = *(const LAS bf16x8*)(Ks + (kvh * 192 + tt * 32 + ql) * 72 + st * 16 + hf * 8);
;                         sa = __builtin_amdgcn_mfma_f32_32x32x16_bf16(kf, qf[st], sa, 0, 0, 0); }
; #pragma unroll
;                     for (int i = 0; i < 16; ++i) sv[t3][i] = sa[i]; }
;                 float mn = mx;
; #pragma unroll
;                 for (int t3 = 0; t3 < 1; ++t3)
; #pragma unroll
;                     for (int i = 0; i < 16; ++i) { const int s = (ps + t3) * 32 + crow(i, hf); float v = sv[t3][i] + blh[s]; if (s < nmask) v = -1e30f; sv[t3][i] = v; mn = fmaxf(mn, v); }
;                 mn = fmaxf(mn, __shfl_xor(mn, 32));
;                 const float resc = __expf(mx - mn); mx = mn;
;                 float psum = 0.f;
; #pragma unroll
;                 for (int t3 = 0; t3 < 1; ++t3)
; #pragma unroll
;                     for (int i = 0; i < 16; ++i) { const float p = __expf(sv[t3][i] - mx); sv[t3][i] = p; psum += p; }
	v_pk_mul_f32 v[4:5], v[8:9], v[94:95]
	s_nop 0
	v_cvt_pk_bf16_f32 v130, v4, v5
	v_pk_mul_f32 v[4:5], v[40:41], v[34:35] op_sel_hi:[0,1]
	v_pk_mul_f32 v[4:5], v[4:5], v[96:97]
	s_nop 0
	v_cvt_pk_bf16_f32 v131, v4, v5
	v_pk_mul_f32 v[4:5], v[40:41], v[36:37] op_sel_hi:[0,1]
	v_pk_mul_f32 v[0:1], v[4:5], v[90:91]
	s_nop 0
	v_cvt_pk_bf16_f32 v132, v0, v1
	v_pk_mul_f32 v[0:1], v[40:41], v[38:39] op_sel_hi:[0,1]
	v_pk_mul_f32 v[0:1], v[0:1], v[92:93]
	s_nop 0
	v_cvt_pk_bf16_f32 v133, v0, v1
	ds_read_b128 v[0:3], v213
	ds_read_b128 v[16:19], v213 offset:32
	ds_read_b128 v[92:95], v213 offset:64
	ds_read_b128 v[96:99], v213 offset:96
	ds_read2_b32 v[74:75], v229 offset0:63 offset1:64
	ds_read2_b32 v[76:77], v229 offset0:65 offset1:66
	ds_read2_b32 v[78:79], v229 offset0:71 offset1:72
	ds_read2_b32 v[80:81], v229 offset0:73 offset1:74
	ds_read2_b32 v[82:83], v229 offset0:79 offset1:80
	ds_read2_b32 v[84:85], v229 offset0:81 offset1:82
	ds_read2_b32 v[86:87], v229 offset0:87 offset1:88
	ds_read2_b32 v[88:89], v229 offset0:89 offset1:90
	s_waitcnt lgkmcnt(11)
	v_mfma_f32_32x32x16_bf16 v[0:15], v[0:3], v[138:141], 0
	s_waitcnt lgkmcnt(10)
	v_mfma_f32_32x32x16_bf16 v[0:15], v[16:19], v[142:145], v[0:15]
	s_waitcnt lgkmcnt(9)
	v_mfma_f32_32x32x16_bf16 v[0:15], v[92:95], v[134:137], v[0:15]
	s_waitcnt lgkmcnt(8)
	v_mfma_f32_32x32x16_bf16 v[0:15], v[96:99], v[130:133], v[0:15]
	s_waitcnt lgkmcnt(0)
	s_nop 10
	v_add_f32_e32 v0, v0, v74
	v_cndmask_b32_e64 v16, v0, v218, s[90:91]
	v_readlane_b32 s90, v254, 53
	v_add_f32_e32 v0, v1, v75
	v_readlane_b32 s91, v254, 54
	s_nop 1
	v_cndmask_b32_e64 v17, v0, v218, s[90:91]
	v_readlane_b32 s90, v254, 55
	v_readlane_b32 s91, v254, 56
	s_waitcnt vmcnt(0)
	v_max3_f32 v18, v228, v16, v17
	s_waitcnt lgkmcnt(0)
	v_add_f32_e32 v0, v2, v76
	v_cndmask_b32_e64 v2, v0, v218, s[90:91]
	v_readlane_b32 s90, v254, 57
	v_add_f32_e32 v0, v3, v77
	v_readlane_b32 s91, v254, 58
	s_nop 1
	v_cndmask_b32_e64 v3, v0, v218, s[90:91]
	v_readlane_b32 s90, v254, 61
	v_readlane_b32 s91, v254, 62
	v_max3_f32 v18, v18, v2, v3
	s_waitcnt lgkmcnt(0)
	v_add_f32_e32 v0, v4, v78
	v_cndmask_b32_e64 v4, v0, v218, s[90:91]
	v_readlane_b32 s90, v255, 7
	v_add_f32_e32 v0, v5, v79
	v_readlane_b32 s91, v255, 8
	s_nop 1
	v_cndmask_b32_e64 v5, v0, v218, s[90:91]
	v_readlane_b32 s90, v255, 5
	v_readlane_b32 s91, v255, 6
	v_max3_f32 v18, v18, v4, v5
	s_waitcnt lgkmcnt(0)
	v_add_f32_e32 v0, v6, v80
	v_cndmask_b32_e64 v6, v0, v218, s[90:91]
	v_readlane_b32 s90, v255, 9
	v_add_f32_e32 v0, v7, v81
	v_readlane_b32 s91, v255, 10
	s_nop 1
	v_cndmask_b32_e64 v7, v0, v218, s[90:91]
	v_readlane_b32 s90, v255, 11
	v_readlane_b32 s91, v255, 12
	v_max3_f32 v18, v18, v6, v7
	s_waitcnt lgkmcnt(0)
	v_add_f32_e32 v0, v8, v82
	v_cndmask_b32_e64 v8, v0, v218, s[90:91]
	v_readlane_b32 s90, v255, 13
	v_add_f32_e32 v0, v9, v83
	v_readlane_b32 s91, v255, 14
	s_nop 1
	v_cndmask_b32_e64 v9, v0, v218, s[90:91]
	v_readlane_b32 s90, v255, 17
	v_readlane_b32 s91, v255, 18
	v_max3_f32 v18, v18, v8, v9
	s_waitcnt lgkmcnt(0)
	v_add_f32_e32 v0, v10, v84
	v_cndmask_b32_e64 v10, v0, v218, s[90:91]
	v_readlane_b32 s90, v255, 15
	v_add_f32_e32 v0, v11, v85
	v_readlane_b32 s91, v255, 16
	s_nop 1
	v_cndmask_b32_e64 v11, v0, v218, s[90:91]
	v_readlane_b32 s90, v255, 21
	v_readlane_b32 s91, v255, 22
	v_max3_f32 v18, v18, v10, v11
	s_waitcnt lgkmcnt(0)
	v_add_f32_e32 v0, v12, v86
	v_cndmask_b32_e64 v12, v0, v218, s[90:91]
	v_readlane_b32 s90, v255, 19
	v_add_f32_e32 v0, v13, v87
	v_readlane_b32 s91, v255, 20
	s_nop 1
	v_cndmask_b32_e64 v13, v0, v218, s[90:91]
	v_readlane_b32 s90, v255, 23
	v_readlane_b32 s91, v255, 24
	v_max3_f32 v18, v18, v12, v13
	ds_read2_b64 v[34:37], v153 offset1:2
	ds_read2_b64 v[194:197], v153 offset0:4 offset1:6
	s_waitcnt lgkmcnt(2)
	v_add_f32_e32 v0, v14, v88
	v_cndmask_b32_e64 v0, v0, v218, s[90:91]
	v_readlane_b32 s90, v254, 63
	v_add_f32_e32 v1, v15, v89
	v_readlane_b32 s91, v255, 0
	ds_read2_b64 v[198:201], v230 offset0:64 offset1:66
	ds_read2_b64 v[202:205], v230 offset0:68 offset1:70
	v_cndmask_b32_e64 v1, v1, v218, s[90:91]
	v_max3_f32 v14, v18, v0, v1
	ds_bpermute_b32 v15, v171, v14
	v_readlane_b32 s90, v255, 1
	v_readlane_b32 s91, v255, 2
	s_waitcnt lgkmcnt(0)
	v_max_f32_e32 v15, v15, v15
	v_max_f32_e32 v51, v14, v15
	v_sub_f32_e32 v2, v2, v51
	v_mul_f32_e32 v2, 0x3fb8aa3b, v2
	v_exp_f32_e32 v50, v2
	v_sub_f32_e32 v2, v3, v51
	v_mul_f32_e32 v2, 0x3fb8aa3b, v2
	v_exp_f32_e32 v52, v2
	v_sub_f32_e32 v2, v4, v51
	v_mul_f32_e32 v2, 0x3fb8aa3b, v2
	v_exp_f32_e32 v54, v2
	v_sub_f32_e32 v2, v5, v51
	v_mul_f32_e32 v2, 0x3fb8aa3b, v2
	v_exp_f32_e32 v56, v2
	v_sub_f32_e32 v2, v6, v51
	v_mul_f32_e32 v2, 0x3fb8aa3b, v2
	v_exp_f32_e32 v58, v2
	v_sub_f32_e32 v2, v7, v51
	v_mul_f32_e32 v2, 0x3fb8aa3b, v2
	v_exp_f32_e32 v60, v2
	v_sub_f32_e32 v2, v8, v51
	v_mul_f32_e32 v2, 0x3fb8aa3b, v2
	v_exp_f32_e32 v62, v2
	v_sub_f32_e32 v2, v9, v51
	v_mul_f32_e32 v2, 0x3fb8aa3b, v2
	v_sub_f32_e32 v0, v0, v51
	v_sub_f32_e32 v15, v16, v51
	v_exp_f32_e32 v64, v2
	v_sub_f32_e32 v2, v10, v51
	v_mul_f32_e32 v0, 0x3fb8aa3b, v0
	v_sub_f32_e32 v14, v228, v51
	v_mul_f32_e32 v15, 0x3fb8aa3b, v15
	v_mul_f32_e32 v2, 0x3fb8aa3b, v2
	v_exp_f32_e32 v186, v0
	v_sub_f32_e32 v0, v1, v51
	v_mul_f32_e32 v14, 0x3fb8aa3b, v14
	v_exp_f32_e32 v16, v15
	v_sub_f32_e32 v15, v17, v51
	v_exp_f32_e32 v178, v2
	v_sub_f32_e32 v2, v11, v51
	v_mul_f32_e32 v0, 0x3fb8aa3b, v0
	v_mul_f32_e32 v15, 0x3fb8aa3b, v15
	v_mul_f32_e32 v2, 0x3fb8aa3b, v2
	v_exp_f32_e32 v188, v0
	v_exp_f32_e32 v0, v14
	v_exp_f32_e32 v17, v15
	v_exp_f32_e32 v180, v2
	v_sub_f32_e32 v2, v12, v51
	v_mul_f32_e32 v2, 0x3fb8aa3b, v2
	v_exp_f32_e32 v182, v2
; #define LAS __attribute__((address_space(3)))
; __device__ __forceinline__ void attn_phase(CArgs a, int l, LAS unsigned char* lds, int tid, int lane, int wave, int G, int bx) {
;     ...
;                     for (int st = 0; st < 4; ++st) { const bf16x8 kf = *(const LAS bf16x8*)(Ks + (kvh * 192 + tt * 32 + ql) * 72 + st * 16 + hf * 8);
;                         sa = __builtin_amdgcn_mfma_f32_32x32x16_bf16(kf, qf[st], sa, 0, 0, 0); }
; #pragma unroll
;                     for (int i = 0; i < 16; ++i) sv[t3][i] = sa[i]; }
;                 float mn = mx;
; #pragma unroll
;                 for (int t3 = 0; t3 < 1; ++t3)
; #pragma unroll
;                     for (int i = 0; i < 16; ++i) { const int s = (ps + t3) * 32 + crow(i, hf); float v = sv[t3][i] + blh[s]; if (s < nmask) v = -1e30f; sv[t3][i] = v; mn = fmaxf(mn, v); }
;                 mn = fmaxf(mn, __shfl_xor(mn, 32));
;                 const float resc = __expf(mx - mn); mx = mn;
;                 float psum = 0.f;
; #pragma unroll
;                 for (int t3 = 0; t3 < 1; ++t3)
; #pragma unroll
;                     for (int i = 0; i < 16; ++i) { const float p = __expf(sv[t3][i] - mx); sv[t3][i] = p; psum += p; }
;                 sum = sum * resc + psum;
;                 o0 = o0 * resc; o1 = o1 * resc;
; #pragma unroll
;                 for (int t3 = 0; t3 < 1; ++t3)
; #pragma unroll
;                     for (int bb = 0; bb < 2; ++bb) { const int tt = ps + t3;
;                         u32x4 pw; pw.x = pk2(sv[t3][8 * bb], sv[t3][8 * bb + 1]); pw.y = pk2(sv[t3][8 * bb + 2], sv[t3][8 * bb + 3]); pw.z = pk2(sv[t3][8 * bb + 4], sv[t3][8 * bb + 5]); pw.w = pk2(sv[t3][8 * bb + 6], sv[t3][8 * bb + 7]);
;                         const bf16x8 pf = __builtin_bit_cast(bf16x8, pw);
;                         const LAS bf16_t* v0p = Vt + (kvh * 64 + ql) * 200 + tt * 32 + 16 * bb + 4 * hf;
;                         const LAS bf16_t* v1p = v0p + 32 * 200;
;                         u32x4 a0, a1; { const u32x2 lo = *(const LAS u32x2*)v0p, hi = *(const LAS u32x2*)(v0p + 8); a0.x = lo.x; a0.y = lo.y; a0.z = hi.x; a0.w = hi.y; }
;                         { const u32x2 lo = *(const LAS u32x2*)v1p, hi = *(const LAS u32x2*)(v1p + 8); a1.x = lo.x; a1.y = lo.y; a1.z = hi.x; a1.w = hi.y; }
;                         o0 = __builtin_amdgcn_mfma_f32_32x32x16_bf16(__builtin_bit_cast(bf16x8, a0), pf, o0, 0, 0, 0);
	v_sub_f32_e32 v2, v13, v51
	v_mul_f32_e32 v2, 0x3fb8aa3b, v2
	v_mul_f32_e32 v0, 0, v0
	v_exp_f32_e32 v184, v2
	v_mov_b32_e32 v1, v0
	v_mov_b32_e32 v2, v0
	v_mov_b32_e32 v3, v0
	v_mov_b32_e32 v4, v0
	v_mov_b32_e32 v5, v0
	v_mov_b32_e32 v6, v0
	v_mov_b32_e32 v7, v0
	v_mov_b32_e32 v8, v0
	v_mov_b32_e32 v9, v0
	v_mov_b32_e32 v10, v0
	v_mov_b32_e32 v11, v0
	v_mov_b32_e32 v12, v0
	v_mov_b32_e32 v13, v0
	v_mov_b32_e32 v14, v0
	v_mov_b32_e32 v15, v0
	v_cvt_pk_bf16_f32 v190, v16, v17
	v_cvt_pk_bf16_f32 v191, v50, v52
	v_cvt_pk_bf16_f32 v192, v54, v56
	v_cvt_pk_bf16_f32 v193, v58, v60
	s_nop 1
	v_mfma_f32_32x32x16_bf16 v[18:33], v[34:37], v[190:193], v[0:15]
	v_mov_b64_e32 v[48:49], v[14:15]
	v_mov_b64_e32 v[46:47], v[12:13]
	v_mov_b64_e32 v[44:45], v[10:11]
	v_mov_b64_e32 v[42:43], v[8:9]
	v_mov_b64_e32 v[40:41], v[6:7]
	v_mov_b64_e32 v[38:39], v[4:5]
	v_mov_b64_e32 v[36:37], v[2:3]
	v_mov_b64_e32 v[34:35], v[0:1]
	v_cvt_pk_bf16_f32 v2, v62, v64
	v_cvt_pk_bf16_f32 v3, v178, v180
	v_mfma_f32_32x32x16_bf16 v[34:49], v[198:201], v[190:193], v[34:49]
	v_cvt_pk_bf16_f32 v4, v182, v184
	v_cvt_pk_bf16_f32 v5, v186, v188
	v_add_f32_e32 v1, 0, v16
	v_add_f32_e32 v160, v17, v1
	v_mfma_f32_32x32x16_bf16 v[18:33], v[194:197], v[2:5], v[18:33]
	v_mfma_f32_32x32x16_bf16 v[34:49], v[202:205], v[2:5], v[34:49]
	ds_read_b128 v[2:5], v213 offset:4608
	ds_read_b128 v[190:193], v213 offset:4640
	ds_read_b128 v[92:95], v213 offset:4672
	ds_read_b128 v[96:99], v213 offset:4704
	ds_read2_b32 v[100:101], v229 offset0:95 offset1:96
	ds_read2_b32 v[102:103], v229 offset0:97 offset1:98
	ds_read2_b32 v[104:105], v229 offset0:103 offset1:104
	ds_read2_b32 v[106:107], v229 offset0:105 offset1:106
	ds_read2_b32 v[108:109], v229 offset0:111 offset1:112
	ds_read2_b32 v[110:111], v229 offset0:113 offset1:114
	ds_read2_b32 v[112:113], v229 offset0:119 offset1:120
	ds_read2_b32 v[90:91], v229 offset0:121 offset1:122
	s_waitcnt lgkmcnt(11)
	v_mfma_f32_32x32x16_bf16 v[2:17], v[2:5], v[138:141], 0
	s_waitcnt lgkmcnt(10)
	v_mfma_f32_32x32x16_bf16 v[2:17], v[190:193], v[142:145], v[2:17]
	s_waitcnt lgkmcnt(9)
	v_mfma_f32_32x32x16_bf16 v[2:17], v[92:95], v[134:137], v[2:17]
	s_waitcnt lgkmcnt(8)
	v_mfma_f32_32x32x16_bf16 v[2:17], v[96:99], v[130:133], v[2:17]
	s_waitcnt lgkmcnt(0)
	s_nop 10
	v_add_f32_e32 v1, v2, v100
	v_cndmask_b32_e64 v1, v1, v218, s[90:91]
	v_readlane_b32 s90, v254, 59
	v_add_f32_e32 v2, v3, v101
	v_readlane_b32 s91, v254, 60
	s_nop 1
	v_cndmask_b32_e64 v53, v2, v218, s[90:91]
	v_readlane_b32 s90, v254, 51
	v_readlane_b32 s91, v254, 52
	v_max3_f32 v55, v51, v1, v53
	s_waitcnt lgkmcnt(0)
	v_add_f32_e32 v2, v4, v102
	v_cndmask_b32_e64 v4, v2, v218, s[90:91]
	v_readlane_b32 s90, v255, 49
	v_add_f32_e32 v2, v5, v103
	v_readlane_b32 s91, v255, 50
	s_nop 1
	v_cndmask_b32_e64 v5, v2, v218, s[90:91]
	v_max3_f32 v55, v55, v4, v5
	s_waitcnt lgkmcnt(0)
	v_add_f32_e32 v2, v6, v104
	v_cndmask_b32_e64 v6, v2, v218, s[92:93]
	v_add_f32_e32 v2, v7, v105
	v_cndmask_b32_e64 v7, v2, v218, s[94:95]
	v_max3_f32 v55, v55, v6, v7
	s_waitcnt lgkmcnt(0)
	v_add_f32_e32 v2, v8, v106
	v_cndmask_b32_e64 v8, v2, v218, s[96:97]
	v_add_f32_e32 v2, v9, v107
	v_cndmask_b32_e64 v9, v2, v218, s[84:85]
	v_max3_f32 v55, v55, v8, v9
	s_waitcnt lgkmcnt(0)
	v_add_f32_e32 v2, v10, v108
	v_cndmask_b32_e64 v10, v2, v218, s[4:5]
	v_add_f32_e32 v2, v11, v109
	v_cndmask_b32_e64 v11, v2, v218, s[6:7]
	v_max3_f32 v55, v55, v10, v11
	s_waitcnt lgkmcnt(0)
	v_add_f32_e32 v2, v12, v110
	v_cndmask_b32_e64 v12, v2, v218, s[8:9]
	v_add_f32_e32 v2, v13, v111
	v_cndmask_b32_e64 v13, v2, v218, s[10:11]
	v_max3_f32 v55, v55, v12, v13
	s_waitcnt lgkmcnt(0)
	v_add_f32_e32 v2, v14, v112
	v_cndmask_b32_e64 v14, v2, v218, s[12:13]
	v_add_f32_e32 v2, v15, v113
	v_cndmask_b32_e64 v15, v2, v218, s[14:15]
	v_max3_f32 v55, v55, v14, v15
	s_waitcnt lgkmcnt(0)
	v_add_f32_e32 v2, v16, v90
	v_add_f32_e32 v3, v17, v91
	v_cndmask_b32_e64 v2, v2, v218, s[16:17]
	v_cndmask_b32_e64 v3, v3, v218, s[18:19]
	v_max3_f32 v16, v55, v2, v3
	ds_bpermute_b32 v17, v171, v16
	s_waitcnt lgkmcnt(0)
	v_max_f32_e32 v17, v17, v17
	v_max_f32_e32 v191, v16, v17
	v_sub_f32_e32 v1, v1, v191
	v_mul_f32_e32 v1, 0x3fb8aa3b, v1
	v_sub_f32_e32 v16, v51, v191
	v_exp_f32_e32 v51, v1
	v_sub_f32_e32 v1, v53, v191
	v_mul_f32_e32 v1, 0x3fb8aa3b, v1
	v_exp_f32_e32 v53, v1
	v_sub_f32_e32 v1, v4, v191
	v_mul_f32_e32 v1, 0x3fb8aa3b, v1
	v_exp_f32_e32 v55, v1
	v_sub_f32_e32 v1, v5, v191
	v_mul_f32_e32 v1, 0x3fb8aa3b, v1
	v_exp_f32_e32 v57, v1
	v_sub_f32_e32 v1, v6, v191
	v_mul_f32_e32 v1, 0x3fb8aa3b, v1
	v_exp_f32_e32 v59, v1
	v_sub_f32_e32 v1, v7, v191
	v_mul_f32_e32 v1, 0x3fb8aa3b, v1
	v_exp_f32_e32 v61, v1
	v_sub_f32_e32 v1, v8, v191
	v_mul_f32_e32 v1, 0x3fb8aa3b, v1
	v_exp_f32_e32 v63, v1
	v_sub_f32_e32 v1, v9, v191
	v_mul_f32_e32 v1, 0x3fb8aa3b, v1
	v_exp_f32_e32 v65, v1
	v_sub_f32_e32 v1, v10, v191
	v_mul_f32_e32 v1, 0x3fb8aa3b, v1
	v_exp_f32_e32 v179, v1
	v_sub_f32_e32 v1, v11, v191
	v_mul_f32_e32 v1, 0x3fb8aa3b, v1
	v_exp_f32_e32 v181, v1
	v_sub_f32_e32 v1, v12, v191
	v_mul_f32_e32 v1, 0x3fb8aa3b, v1
	v_mul_f32_e32 v16, 0x3fb8aa3b, v16
	v_exp_f32_e32 v183, v1
	v_sub_f32_e32 v1, v13, v191
	v_mul_f32_e32 v1, 0x3fb8aa3b, v1
	v_exp_f32_e32 v190, v16
	v_exp_f32_e32 v185, v1
	v_sub_f32_e32 v1, v14, v191
	v_mul_f32_e32 v1, 0x3fb8aa3b, v1
	v_exp_f32_e32 v187, v1
	v_sub_f32_e32 v1, v15, v191
	v_mul_f32_e32 v1, 0x3fb8aa3b, v1
	v_pk_mul_f32 v[16:17], v[32:33], v[190:191] op_sel_hi:[1,0]
	v_pk_mul_f32 v[14:15], v[30:31], v[190:191] op_sel_hi:[1,0]
	v_pk_mul_f32 v[12:13], v[28:29], v[190:191] op_sel_hi:[1,0]
	v_pk_mul_f32 v[10:11], v[26:27], v[190:191] op_sel_hi:[1,0]
	v_pk_mul_f32 v[8:9], v[24:25], v[190:191] op_sel_hi:[1,0]
	v_pk_mul_f32 v[6:7], v[22:23], v[190:191] op_sel_hi:[1,0]
	v_pk_mul_f32 v[32:33], v[48:49], v[190:191] op_sel_hi:[1,0]
	v_pk_mul_f32 v[30:31], v[46:47], v[190:191] op_sel_hi:[1,0]
	v_pk_mul_f32 v[28:29], v[44:45], v[190:191] op_sel_hi:[1,0]
	v_pk_mul_f32 v[26:27], v[42:43], v[190:191] op_sel_hi:[1,0]
	v_pk_mul_f32 v[24:25], v[40:41], v[190:191] op_sel_hi:[1,0]
	v_pk_mul_f32 v[22:23], v[38:39], v[190:191] op_sel_hi:[1,0]
	ds_read2_b64 v[38:41], v153 offset0:8 offset1:10
	ds_read2_b64 v[42:45], v153 offset0:12 offset1:14
	ds_read2_b64 v[46:49], v230 offset0:72 offset1:74
	ds_read2_b64 v[192:195], v230 offset0:76 offset1:78
	v_exp_f32_e32 v189, v1
	v_sub_f32_e32 v1, v2, v191
	v_sub_f32_e32 v2, v3, v191
	v_mul_f32_e32 v2, 0x3fb8aa3b, v2
	v_exp_f32_e32 v196, v2
	v_pk_mul_f32 v[4:5], v[20:21], v[190:191] op_sel_hi:[1,0]
	v_pk_mul_f32 v[2:3], v[18:19], v[190:191] op_sel_hi:[1,0]
	v_pk_mul_f32 v[20:21], v[36:37], v[190:191] op_sel_hi:[1,0]
	v_pk_mul_f32 v[18:19], v[34:35], v[190:191] op_sel_hi:[1,0]
	v_cvt_pk_bf16_f32 v34, v51, v53
	v_cvt_pk_bf16_f32 v35, v55, v57
	v_cvt_pk_bf16_f32 v36, v59, v61
	v_cvt_pk_bf16_f32 v37, v63, v65
	v_mul_f32_e32 v1, 0x3fb8aa3b, v1
	v_exp_f32_e32 v1, v1
	s_waitcnt lgkmcnt(3)
; #define LAS __attribute__((address_space(3)))
; __device__ __forceinline__ void attn_phase(CArgs a, int l, LAS unsigned char* lds, int tid, int lane, int wave, int G, int bx) {
;     ...
;                     for (int st = 0; st < 4; ++st) { const bf16x8 kf = *(const LAS bf16x8*)(Ks + (kvh * 192 + tt * 32 + ql) * 72 + st * 16 + hf * 8);
;                         sa = __builtin_amdgcn_mfma_f32_32x32x16_bf16(kf, qf[st], sa, 0, 0, 0); }
; #pragma unroll
;                     for (int i = 0; i < 16; ++i) sv[t3][i] = sa[i]; }
;                 float mn = mx;
; #pragma unroll
;                 for (int t3 = 0; t3 < 1; ++t3)
; #pragma unroll
;                     for (int i = 0; i < 16; ++i) { const int s = (ps + t3) * 32 + crow(i, hf); float v = sv[t3][i] + blh[s]; if (s < nmask) v = -1e30f; sv[t3][i] = v; mn = fmaxf(mn, v); }
;                 mn = fmaxf(mn, __shfl_xor(mn, 32));
;                 const float resc = __expf(mx - mn); mx = mn;
;                 float psum = 0.f;
; #pragma unroll
;                 for (int t3 = 0; t3 < 1; ++t3)
; #pragma unroll
;                     for (int i = 0; i < 16; ++i) { const float p = __expf(sv[t3][i] - mx); sv[t3][i] = p; psum += p; }
;                 sum = sum * resc + psum;
;                 o0 = o0 * resc; o1 = o1 * resc;
; #pragma unroll
;                 for (int t3 = 0; t3 < 1; ++t3)
; #pragma unroll
;                     for (int bb = 0; bb < 2; ++bb) { const int tt = ps + t3;
;                         u32x4 pw; pw.x = pk2(sv[t3][8 * bb], sv[t3][8 * bb + 1]); pw.y = pk2(sv[t3][8 * bb + 2], sv[t3][8 * bb + 3]); pw.z = pk2(sv[t3][8 * bb + 4], sv[t3][8 * bb + 5]); pw.w = pk2(sv[t3][8 * bb + 6], sv[t3][8 * bb + 7]);
;                         const bf16x8 pf = __builtin_bit_cast(bf16x8, pw);
;                         const LAS bf16_t* v0p = Vt + (kvh * 64 + ql) * 200 + tt * 32 + 16 * bb + 4 * hf;
;                         const LAS bf16_t* v1p = v0p + 32 * 200;
;                         u32x4 a0, a1; { const u32x2 lo = *(const LAS u32x2*)v0p, hi = *(const LAS u32x2*)(v0p + 8); a0.x = lo.x; a0.y = lo.y; a0.z = hi.x; a0.w = hi.y; }
;                         { const u32x2 lo = *(const LAS u32x2*)v1p, hi = *(const LAS u32x2*)(v1p + 8); a1.x = lo.x; a1.y = lo.y; a1.z = hi.x; a1.w = hi.y; }
;                         o0 = __builtin_amdgcn_mfma_f32_32x32x16_bf16(__builtin_bit_cast(bf16x8, a0), pf, o0, 0, 0, 0);
	v_mfma_f32_32x32x16_bf16 v[2:17], v[38:41], v[34:37], v[2:17]
	s_waitcnt lgkmcnt(1)
	v_mfma_f32_32x32x16_bf16 v[18:33], v[46:49], v[34:37], v[18:33]
	v_cvt_pk_bf16_f32 v34, v179, v181
	v_cvt_pk_bf16_f32 v35, v183, v185
	v_cvt_pk_bf16_f32 v36, v187, v189
	v_cvt_pk_bf16_f32 v37, v1, v196
	s_nop 1
	v_mfma_f32_32x32x16_bf16 v[2:17], v[42:45], v[34:37], v[2:17]
	s_waitcnt lgkmcnt(0)
	v_mfma_f32_32x32x16_bf16 v[18:33], v[192:195], v[34:37], v[18:33]
	v_add_f32_e64 v34, v50, v160
	v_add_f32_e64 v35, v51, v161
	v_add_f32_e64 v34, v52, v34
	v_add_f32_e64 v35, v53, v35
	v_add_f32_e64 v34, v54, v34
	v_add_f32_e64 v35, v55, v35
	v_pk_add_f32 v[34:35], v[56:57], v[34:35]
	s_nop 0
	v_pk_add_f32 v[34:35], v[58:59], v[34:35]
	s_nop 0
	v_pk_add_f32 v[34:35], v[60:61], v[34:35]
	s_nop 0
	v_pk_add_f32 v[34:35], v[62:63], v[34:35]
	s_nop 0
	v_pk_add_f32 v[34:35], v[64:65], v[34:35]
	s_nop 0
	v_pk_add_f32 v[34:35], v[178:179], v[34:35]
	s_nop 0
	v_pk_add_f32 v[34:35], v[180:181], v[34:35]
	s_nop 0
	v_pk_add_f32 v[34:35], v[182:183], v[34:35]
	s_nop 0
	v_pk_add_f32 v[34:35], v[184:185], v[34:35]
	s_nop 0
	v_pk_add_f32 v[34:35], v[186:187], v[34:35]
	s_nop 0
	v_pk_add_f32 v[34:35], v[188:189], v[34:35]
	s_nop 0
	v_pk_add_f32 v[0:1], v[0:1], v[34:35]
	ds_read_b128 v[34:37], v213 offset:9216
	ds_read_b128 v[50:53], v213 offset:9248
	ds_read_b128 v[92:95], v213 offset:9280
	ds_read_b128 v[96:99], v213 offset:9312
	ds_read2_b32 v[74:75], v229 offset0:127 offset1:128
	ds_read2_b32 v[76:77], v229 offset0:129 offset1:130
	ds_read2_b32 v[78:79], v229 offset0:135 offset1:136
	ds_read2_b32 v[80:81], v229 offset0:137 offset1:138
	ds_read2_b32 v[82:83], v229 offset0:143 offset1:144
	ds_read2_b32 v[84:85], v229 offset0:145 offset1:146
	ds_read2_b32 v[86:87], v229 offset0:151 offset1:152
	ds_read2_b32 v[88:89], v229 offset0:153 offset1:154
	s_waitcnt lgkmcnt(11)
	v_mfma_f32_32x32x16_bf16 v[34:49], v[34:37], v[138:141], 0
	v_add_f32_e32 v54, v1, v196
	v_fmac_f32_e32 v54, v0, v190
	s_waitcnt lgkmcnt(10)
	v_mfma_f32_32x32x16_bf16 v[34:49], v[50:53], v[142:145], v[34:49]
	s_waitcnt lgkmcnt(9)
	v_mfma_f32_32x32x16_bf16 v[34:49], v[92:95], v[134:137], v[34:49]
	s_waitcnt lgkmcnt(8)
	v_mfma_f32_32x32x16_bf16 v[34:49], v[96:99], v[130:133], v[34:49]
	s_waitcnt lgkmcnt(0)
	s_nop 10
	v_add_f32_e32 v0, v34, v74
	v_cndmask_b32_e64 v34, v0, v218, s[20:21]
	v_add_f32_e32 v0, v35, v75
	v_cndmask_b32_e64 v35, v0, v218, s[22:23]
	v_max3_f32 v50, v191, v34, v35
	s_waitcnt lgkmcnt(0)
	v_add_f32_e32 v0, v36, v76
	v_cndmask_b32_e64 v36, v0, v218, s[24:25]
	v_add_f32_e32 v0, v37, v77
	v_cndmask_b32_e64 v37, v0, v218, s[26:27]
	v_max3_f32 v50, v50, v36, v37
	s_waitcnt lgkmcnt(0)
	v_add_f32_e32 v0, v38, v78
	v_cndmask_b32_e64 v38, v0, v218, s[28:29]
	v_add_f32_e32 v0, v39, v79
	v_cndmask_b32_e64 v39, v0, v218, s[30:31]
	v_max3_f32 v50, v50, v38, v39
	s_waitcnt lgkmcnt(0)
	v_add_f32_e32 v0, v40, v80
	v_cndmask_b32_e64 v40, v0, v218, s[34:35]
	v_add_f32_e32 v0, v41, v81
	v_cndmask_b32_e64 v41, v0, v218, s[36:37]
	v_max3_f32 v50, v50, v40, v41
	s_waitcnt lgkmcnt(0)
	v_add_f32_e32 v0, v42, v82
	v_cndmask_b32_e64 v42, v0, v218, s[46:47]
	v_add_f32_e32 v0, v43, v83
	v_cndmask_b32_e64 v43, v0, v218, s[0:1]
	v_max3_f32 v50, v50, v42, v43
	s_waitcnt lgkmcnt(0)
	v_add_f32_e32 v0, v44, v84
	v_cndmask_b32_e64 v44, v0, v218, s[48:49]
	v_add_f32_e32 v0, v45, v85
	v_cndmask_b32_e64 v45, v0, v218, s[50:51]
	v_max3_f32 v50, v50, v44, v45
	s_waitcnt lgkmcnt(0)
	v_add_f32_e32 v0, v46, v86
	v_cndmask_b32_e64 v46, v0, v218, s[40:41]
	v_add_f32_e32 v0, v47, v87
	v_cndmask_b32_e64 v47, v0, v218, s[42:43]
	v_max3_f32 v50, v50, v46, v47
	s_waitcnt lgkmcnt(0)
	v_add_f32_e32 v0, v48, v88
	v_add_f32_e32 v1, v49, v89
	v_cndmask_b32_e64 v0, v0, v218, s[44:45]
	v_cndmask_b32_e64 v1, v1, v218, s[38:39]
	v_max3_f32 v48, v50, v0, v1
	ds_bpermute_b32 v49, v171, v48
	s_waitcnt lgkmcnt(0)
	v_max_f32_e32 v49, v49, v49
	v_max_f32_e32 v179, v48, v49
	v_sub_f32_e32 v34, v34, v179
	v_mul_f32_e32 v34, 0x3fb8aa3b, v34
	v_exp_f32_e32 v160, v34
	v_sub_f32_e32 v34, v35, v179
	v_mul_f32_e32 v34, 0x3fb8aa3b, v34
	v_exp_f32_e32 v181, v34
	v_sub_f32_e32 v34, v36, v179
	v_mul_f32_e32 v34, 0x3fb8aa3b, v34
	v_exp_f32_e32 v178, v34
	v_sub_f32_e32 v34, v37, v179
	v_mul_f32_e32 v34, 0x3fb8aa3b, v34
	v_exp_f32_e32 v180, v34
	v_sub_f32_e32 v34, v38, v179
	v_mul_f32_e32 v34, 0x3fb8aa3b, v34
	v_exp_f32_e32 v182, v34
	v_sub_f32_e32 v34, v39, v179
	v_mul_f32_e32 v34, 0x3fb8aa3b, v34
	v_exp_f32_e32 v184, v34
	v_sub_f32_e32 v34, v40, v179
	v_mul_f32_e32 v34, 0x3fb8aa3b, v34
	v_exp_f32_e32 v186, v34
	v_sub_f32_e32 v34, v41, v179
	v_mul_f32_e32 v34, 0x3fb8aa3b, v34
	v_exp_f32_e32 v188, v34
	v_sub_f32_e32 v34, v42, v179
	v_mul_f32_e32 v34, 0x3fb8aa3b, v34
	v_exp_f32_e32 v190, v34
	v_sub_f32_e32 v34, v43, v179
	v_sub_f32_e32 v0, v0, v179
	v_mul_f32_e32 v34, 0x3fb8aa3b, v34
	v_mul_f32_e32 v0, 0x3fb8aa3b, v0
	v_sub_f32_e32 v48, v191, v179
	v_exp_f32_e32 v192, v34
	v_sub_f32_e32 v34, v44, v179
	v_exp_f32_e32 v202, v0
	v_sub_f32_e32 v0, v1, v179
	v_mul_f32_e32 v48, 0x3fb8aa3b, v48
	v_mul_f32_e32 v34, 0x3fb8aa3b, v34
	v_mul_f32_e32 v0, 0x3fb8aa3b, v0
	v_exp_f32_e32 v194, v34
	v_sub_f32_e32 v34, v45, v179
	v_exp_f32_e32 v204, v0
	v_exp_f32_e32 v0, v48
	v_mul_f32_e32 v34, 0x3fb8aa3b, v34
	v_exp_f32_e32 v196, v34
	v_sub_f32_e32 v34, v46, v179
	v_mul_f32_e32 v34, 0x3fb8aa3b, v34
	v_exp_f32_e32 v198, v34
	v_sub_f32_e32 v34, v47, v179
	v_pk_mul_f32 v[48:49], v[16:17], v[0:1] op_sel_hi:[1,0]
	v_pk_mul_f32 v[46:47], v[14:15], v[0:1] op_sel_hi:[1,0]
	v_pk_mul_f32 v[44:45], v[12:13], v[0:1] op_sel_hi:[1,0]
	v_pk_mul_f32 v[42:43], v[10:11], v[0:1] op_sel_hi:[1,0]
	v_pk_mul_f32 v[40:41], v[8:9], v[0:1] op_sel_hi:[1,0]
	v_pk_mul_f32 v[38:39], v[6:7], v[0:1] op_sel_hi:[1,0]
	v_pk_mul_f32 v[36:37], v[4:5], v[0:1] op_sel_hi:[1,0]
	v_pk_mul_f32 v[50:51], v[18:19], v[0:1] op_sel_hi:[1,0]
	ds_read2_b64 v[4:7], v153 offset0:16 offset1:18
	ds_read2_b64 v[8:11], v153 offset0:20 offset1:22
	ds_read2_b64 v[12:15], v230 offset0:80 offset1:82
	ds_read2_b64 v[16:19], v230 offset0:84 offset1:86
	v_mul_f32_e32 v34, 0x3fb8aa3b, v34
	v_exp_f32_e32 v200, v34
	v_mul_f32_e32 v206, v54, v0
	v_pk_mul_f32 v[34:35], v[2:3], v[0:1] op_sel_hi:[1,0]
	v_pk_mul_f32 v[64:65], v[32:33], v[0:1] op_sel_hi:[1,0]
	v_pk_mul_f32 v[62:63], v[30:31], v[0:1] op_sel_hi:[1,0]
	v_pk_mul_f32 v[60:61], v[28:29], v[0:1] op_sel_hi:[1,0]
	v_pk_mul_f32 v[58:59], v[26:27], v[0:1] op_sel_hi:[1,0]
	v_pk_mul_f32 v[56:57], v[24:25], v[0:1] op_sel_hi:[1,0]
	v_pk_mul_f32 v[54:55], v[22:23], v[0:1] op_sel_hi:[1,0]
	v_pk_mul_f32 v[52:53], v[20:21], v[0:1] op_sel_hi:[1,0]
	v_cvt_pk_bf16_f32 v0, v160, v181
	v_cvt_pk_bf16_f32 v1, v178, v180
	v_cvt_pk_bf16_f32 v2, v182, v184
	v_cvt_pk_bf16_f32 v3, v186, v188
	s_waitcnt lgkmcnt(3)
; #define LAS __attribute__((address_space(3)))
; __device__ __forceinline__ void attn_phase(CArgs a, int l, LAS unsigned char* lds, int tid, int lane, int wave, int G, int bx) {
;     ...
;                     for (int st = 0; st < 4; ++st) { const bf16x8 kf = *(const LAS bf16x8*)(Ks + (kvh * 192 + tt * 32 + ql) * 72 + st * 16 + hf * 8);
;                         sa = __builtin_amdgcn_mfma_f32_32x32x16_bf16(kf, qf[st], sa, 0, 0, 0); }
; #pragma unroll
;                     for (int i = 0; i < 16; ++i) sv[t3][i] = sa[i]; }
;                 float mn = mx;
; #pragma unroll
;                 for (int t3 = 0; t3 < 1; ++t3)
; #pragma unroll
;                     for (int i = 0; i < 16; ++i) { const int s = (ps + t3) * 32 + crow(i, hf); float v = sv[t3][i] + blh[s]; if (s < nmask) v = -1e30f; sv[t3][i] = v; mn = fmaxf(mn, v); }
;                 mn = fmaxf(mn, __shfl_xor(mn, 32));
;                 const float resc = __expf(mx - mn); mx = mn;
;                 float psum = 0.f;
; #pragma unroll
;                 for (int t3 = 0; t3 < 1; ++t3)
; #pragma unroll
;                     for (int i = 0; i < 16; ++i) { const float p = __expf(sv[t3][i] - mx); sv[t3][i] = p; psum += p; }
;                 sum = sum * resc + psum;
;                 o0 = o0 * resc; o1 = o1 * resc;
; #pragma unroll
;                 for (int t3 = 0; t3 < 1; ++t3)
; #pragma unroll
;                     for (int bb = 0; bb < 2; ++bb) { const int tt = ps + t3;
;                         u32x4 pw; pw.x = pk2(sv[t3][8 * bb], sv[t3][8 * bb + 1]); pw.y = pk2(sv[t3][8 * bb + 2], sv[t3][8 * bb + 3]); pw.z = pk2(sv[t3][8 * bb + 4], sv[t3][8 * bb + 5]); pw.w = pk2(sv[t3][8 * bb + 6], sv[t3][8 * bb + 7]);
;                         const bf16x8 pf = __builtin_bit_cast(bf16x8, pw);
;                         const LAS bf16_t* v0p = Vt + (kvh * 64 + ql) * 200 + tt * 32 + 16 * bb + 4 * hf;
;                         const LAS bf16_t* v1p = v0p + 32 * 200;
;                         u32x4 a0, a1; { const u32x2 lo = *(const LAS u32x2*)v0p, hi = *(const LAS u32x2*)(v0p + 8); a0.x = lo.x; a0.y = lo.y; a0.z = hi.x; a0.w = hi.y; }
;                         { const u32x2 lo = *(const LAS u32x2*)v1p, hi = *(const LAS u32x2*)(v1p + 8); a1.x = lo.x; a1.y = lo.y; a1.z = hi.x; a1.w = hi.y; }
;                         o0 = __builtin_amdgcn_mfma_f32_32x32x16_bf16(__builtin_bit_cast(bf16x8, a0), pf, o0, 0, 0, 0);
	s_nop 0
	v_mfma_f32_32x32x16_bf16 v[34:49], v[4:7], v[0:3], v[34:49]
	s_waitcnt lgkmcnt(1)
	v_mfma_f32_32x32x16_bf16 v[50:65], v[12:15], v[0:3], v[50:65]
	v_cvt_pk_bf16_f32 v0, v190, v192
	v_cvt_pk_bf16_f32 v1, v194, v196
	v_cvt_pk_bf16_f32 v2, v198, v200
	v_cvt_pk_bf16_f32 v3, v202, v204
	s_nop 1
	v_mfma_f32_32x32x16_bf16 v[34:49], v[8:11], v[0:3], v[34:49]
	s_waitcnt lgkmcnt(0)
	v_mfma_f32_32x32x16_bf16 v[50:65], v[16:19], v[0:3], v[50:65]
	v_add_f32_e32 v0, 0, v160
	v_add_f32_e32 v160, v181, v0
	ds_read_b128 v[0:3], v213 offset:13824
	ds_read_b128 v[16:19], v213 offset:13856
	ds_read_b128 v[92:95], v213 offset:13888
	ds_read_b128 v[96:99], v213 offset:13920
	ds_read2_b32 v[100:101], v229 offset0:159 offset1:160
	ds_read2_b32 v[102:103], v229 offset0:161 offset1:162
	ds_read2_b32 v[104:105], v229 offset0:167 offset1:168
	ds_read2_b32 v[106:107], v229 offset0:169 offset1:170
	ds_read2_b32 v[108:109], v229 offset0:175 offset1:176
	ds_read2_b32 v[110:111], v229 offset0:177 offset1:178
	ds_read2_b32 v[112:113], v229 offset0:183 offset1:184
	ds_read2_b32 v[90:91], v229 offset0:185 offset1:186
	s_waitcnt lgkmcnt(11)
	v_mfma_f32_32x32x16_bf16 v[0:15], v[0:3], v[138:141], 0
	s_waitcnt lgkmcnt(10)
	v_mfma_f32_32x32x16_bf16 v[0:15], v[16:19], v[142:145], v[0:15]
	s_waitcnt lgkmcnt(9)
	v_mfma_f32_32x32x16_bf16 v[0:15], v[92:95], v[134:137], v[0:15]
	s_waitcnt lgkmcnt(8)
	v_mfma_f32_32x32x16_bf16 v[0:15], v[96:99], v[130:133], v[0:15]
	s_waitcnt lgkmcnt(0)
	s_nop 10
	v_add_f32_e32 v0, v0, v100
	v_cndmask_b32_e64 v16, v0, v218, s[52:53]
	v_add_f32_e32 v0, v1, v101
	v_cndmask_b32_e64 v17, v0, v218, s[54:55]
	v_max3_f32 v18, v179, v16, v17
	s_waitcnt lgkmcnt(0)
	v_add_f32_e32 v0, v2, v102
	v_cndmask_b32_e64 v2, v0, v218, s[56:57]
	v_add_f32_e32 v0, v3, v103
	v_cndmask_b32_e64 v3, v0, v218, s[58:59]
	v_max3_f32 v18, v18, v2, v3
	s_waitcnt lgkmcnt(0)
	v_add_f32_e32 v0, v4, v104
	v_cndmask_b32_e64 v4, v0, v218, s[60:61]
	v_add_f32_e32 v0, v5, v105
	v_cndmask_b32_e64 v5, v0, v218, s[62:63]
	v_max3_f32 v18, v18, v4, v5
	s_waitcnt lgkmcnt(0)
	v_add_f32_e32 v0, v6, v106
	v_cndmask_b32_e64 v6, v0, v218, s[64:65]
	v_add_f32_e32 v0, v7, v107
	v_cndmask_b32_e64 v7, v0, v218, s[66:67]
	v_max3_f32 v18, v18, v6, v7
	s_waitcnt lgkmcnt(0)
	v_add_f32_e32 v0, v8, v108
	v_cndmask_b32_e64 v8, v0, v218, s[68:69]
	v_add_f32_e32 v0, v9, v109
	v_cndmask_b32_e64 v9, v0, v218, s[70:71]
	v_max3_f32 v18, v18, v8, v9
	s_waitcnt lgkmcnt(0)
	v_add_f32_e32 v0, v10, v110
	v_cndmask_b32_e64 v10, v0, v218, s[72:73]
	v_add_f32_e32 v0, v11, v111
	v_cndmask_b32_e64 v11, v0, v218, s[74:75]
	v_max3_f32 v18, v18, v10, v11
	s_waitcnt lgkmcnt(0)
	v_add_f32_e32 v0, v12, v112
	v_cndmask_b32_e64 v12, v0, v218, s[76:77]
	v_add_f32_e32 v0, v13, v113
	v_cndmask_b32_e64 v13, v0, v218, s[78:79]
	v_max3_f32 v18, v18, v12, v13
	s_waitcnt lgkmcnt(0)
	v_add_f32_e32 v0, v14, v90
	v_add_f32_e32 v1, v15, v91
	v_cndmask_b32_e64 v0, v0, v218, s[80:81]
	v_cndmask_b32_e64 v1, v1, v218, s[82:83]
	v_max3_f32 v14, v18, v0, v1
	ds_bpermute_b32 v15, v171, v14
	s_waitcnt lgkmcnt(0)
	v_max_f32_e32 v15, v15, v15
	v_max_f32_e32 v231, v14, v15
	v_sub_f32_e32 v2, v2, v231
	v_mul_f32_e32 v2, 0x3fb8aa3b, v2
	v_exp_f32_e32 v183, v2
	v_sub_f32_e32 v2, v3, v231
	v_mul_f32_e32 v2, 0x3fb8aa3b, v2
	v_exp_f32_e32 v185, v2
	v_sub_f32_e32 v2, v4, v231
	v_mul_f32_e32 v2, 0x3fb8aa3b, v2
	v_exp_f32_e32 v187, v2
	v_sub_f32_e32 v2, v5, v231
	v_mul_f32_e32 v2, 0x3fb8aa3b, v2
	v_exp_f32_e32 v189, v2
	v_sub_f32_e32 v2, v6, v231
	v_mul_f32_e32 v2, 0x3fb8aa3b, v2
	v_exp_f32_e32 v191, v2
	v_sub_f32_e32 v2, v7, v231
	v_mul_f32_e32 v2, 0x3fb8aa3b, v2
	v_exp_f32_e32 v193, v2
	v_sub_f32_e32 v2, v8, v231
	v_mul_f32_e32 v2, 0x3fb8aa3b, v2
	v_exp_f32_e32 v195, v2
	v_sub_f32_e32 v2, v9, v231
	v_sub_f32_e32 v0, v0, v231
	v_mul_f32_e32 v2, 0x3fb8aa3b, v2
	v_mul_f32_e32 v0, 0x3fb8aa3b, v0
	v_sub_f32_e32 v14, v179, v231
	v_exp_f32_e32 v197, v2
	v_sub_f32_e32 v2, v10, v231
	v_exp_f32_e32 v207, v0
	v_sub_f32_e32 v0, v1, v231
	v_mul_f32_e32 v14, 0x3fb8aa3b, v14
	v_sub_f32_e32 v15, v16, v231
	v_mul_f32_e32 v2, 0x3fb8aa3b, v2
	v_mul_f32_e32 v0, 0x3fb8aa3b, v0
	v_mul_f32_e32 v15, 0x3fb8aa3b, v15
	v_exp_f32_e32 v199, v2
	v_sub_f32_e32 v2, v11, v231
	v_exp_f32_e32 v33, v0
	v_exp_f32_e32 v32, v14
	v_exp_f32_e32 v179, v15
	v_sub_f32_e32 v15, v17, v231
	v_mul_f32_e32 v2, 0x3fb8aa3b, v2
	v_mul_f32_e32 v15, 0x3fb8aa3b, v15
	v_exp_f32_e32 v201, v2
	v_sub_f32_e32 v2, v12, v231
	v_exp_f32_e32 v181, v15
	v_mul_f32_e32 v2, 0x3fb8aa3b, v2
	v_exp_f32_e32 v203, v2
	v_sub_f32_e32 v2, v13, v231
	v_pk_mul_f32 v[14:15], v[48:49], v[32:33] op_sel_hi:[1,0]
	v_pk_mul_f32 v[12:13], v[46:47], v[32:33] op_sel_hi:[1,0]
	v_pk_mul_f32 v[10:11], v[44:45], v[32:33] op_sel_hi:[1,0]
	v_pk_mul_f32 v[8:9], v[42:43], v[32:33] op_sel_hi:[1,0]
	v_pk_mul_f32 v[6:7], v[40:41], v[32:33] op_sel_hi:[1,0]
	v_pk_mul_f32 v[4:5], v[38:39], v[32:33] op_sel_hi:[1,0]
	v_pk_mul_f32 v[18:19], v[52:53], v[32:33] op_sel_hi:[1,0]
	v_pk_mul_f32 v[16:17], v[50:51], v[32:33] op_sel_hi:[1,0]
	ds_read2_b64 v[38:41], v153 offset0:24 offset1:26
	ds_read2_b64 v[42:45], v153 offset0:28 offset1:30
	ds_read2_b64 v[46:49], v230 offset0:88 offset1:90
	ds_read2_b64 v[50:53], v230 offset0:92 offset1:94
	v_mul_f32_e32 v2, 0x3fb8aa3b, v2
	v_exp_f32_e32 v205, v2
	v_pk_mul_f32 v[2:3], v[36:37], v[32:33] op_sel_hi:[1,0]
	v_pk_mul_f32 v[0:1], v[34:35], v[32:33] op_sel_hi:[1,0]
	v_pk_mul_f32 v[30:31], v[64:65], v[32:33] op_sel_hi:[1,0]
	v_pk_mul_f32 v[28:29], v[62:63], v[32:33] op_sel_hi:[1,0]
	v_pk_mul_f32 v[26:27], v[60:61], v[32:33] op_sel_hi:[1,0]
	v_pk_mul_f32 v[24:25], v[58:59], v[32:33] op_sel_hi:[1,0]
	v_pk_mul_f32 v[22:23], v[56:57], v[32:33] op_sel_hi:[1,0]
	v_pk_mul_f32 v[20:21], v[54:55], v[32:33] op_sel_hi:[1,0]
	v_cvt_pk_bf16_f32 v34, v179, v181
	v_cvt_pk_bf16_f32 v35, v183, v185
	v_cvt_pk_bf16_f32 v36, v187, v189
	v_cvt_pk_bf16_f32 v37, v191, v193
	s_waitcnt lgkmcnt(3)
; #define LAS __attribute__((address_space(3)))
; __device__ __forceinline__ void attn_phase(CArgs a, int l, LAS unsigned char* lds, int tid, int lane, int wave, int G, int bx) {
;     ...
;                     for (int st = 0; st < 4; ++st) { const bf16x8 kf = *(const LAS bf16x8*)(Ks + (kvh * 192 + tt * 32 + ql) * 72 + st * 16 + hf * 8);
;                         sa = __builtin_amdgcn_mfma_f32_32x32x16_bf16(kf, qf[st], sa, 0, 0, 0); }
; #pragma unroll
;                     for (int i = 0; i < 16; ++i) sv[t3][i] = sa[i]; }
;                 float mn = mx;
; #pragma unroll
;                 for (int t3 = 0; t3 < 1; ++t3)
; #pragma unroll
;                     for (int i = 0; i < 16; ++i) { const int s = (ps + t3) * 32 + crow(i, hf); float v = sv[t3][i] + blh[s]; if (s < nmask) v = -1e30f; sv[t3][i] = v; mn = fmaxf(mn, v); }
;                 mn = fmaxf(mn, __shfl_xor(mn, 32));
;                 const float resc = __expf(mx - mn); mx = mn;
;                 float psum = 0.f;
; #pragma unroll
;                 for (int t3 = 0; t3 < 1; ++t3)
; #pragma unroll
;                     for (int i = 0; i < 16; ++i) { const float p = __expf(sv[t3][i] - mx); sv[t3][i] = p; psum += p; }
;                 sum = sum * resc + psum;
;                 o0 = o0 * resc; o1 = o1 * resc;
; #pragma unroll
;                 for (int t3 = 0; t3 < 1; ++t3)
; #pragma unroll
;                     for (int bb = 0; bb < 2; ++bb) { const int tt = ps + t3;
;                         u32x4 pw; pw.x = pk2(sv[t3][8 * bb], sv[t3][8 * bb + 1]); pw.y = pk2(sv[t3][8 * bb + 2], sv[t3][8 * bb + 3]); pw.z = pk2(sv[t3][8 * bb + 4], sv[t3][8 * bb + 5]); pw.w = pk2(sv[t3][8 * bb + 6], sv[t3][8 * bb + 7]);
;                         const bf16x8 pf = __builtin_bit_cast(bf16x8, pw);
;                         const LAS bf16_t* v0p = Vt + (kvh * 64 + ql) * 200 + tt * 32 + 16 * bb + 4 * hf;
;                         const LAS bf16_t* v1p = v0p + 32 * 200;
;                         u32x4 a0, a1; { const u32x2 lo = *(const LAS u32x2*)v0p, hi = *(const LAS u32x2*)(v0p + 8); a0.x = lo.x; a0.y = lo.y; a0.z = hi.x; a0.w = hi.y; }
;                         { const u32x2 lo = *(const LAS u32x2*)v1p, hi = *(const LAS u32x2*)(v1p + 8); a1.x = lo.x; a1.y = lo.y; a1.z = hi.x; a1.w = hi.y; }
;                         o0 = __builtin_amdgcn_mfma_f32_32x32x16_bf16(__builtin_bit_cast(bf16x8, a0), pf, o0, 0, 0, 0);
	s_nop 0
	v_mfma_f32_32x32x16_bf16 v[0:15], v[38:41], v[34:37], v[0:15]
	s_waitcnt lgkmcnt(1)
	v_mfma_f32_32x32x16_bf16 v[16:31], v[46:49], v[34:37], v[16:31]
	v_cvt_pk_bf16_f32 v34, v195, v197
	v_cvt_pk_bf16_f32 v35, v199, v201
	v_cvt_pk_bf16_f32 v36, v203, v205
	v_cvt_pk_bf16_f32 v37, v207, v33
	s_nop 1
	v_mfma_f32_32x32x16_bf16 v[0:15], v[42:45], v[34:37], v[0:15]
	s_waitcnt lgkmcnt(0)
	v_mfma_f32_32x32x16_bf16 v[16:31], v[50:53], v[34:37], v[16:31]
	v_add_f32_e64 v34, v178, v160
	v_add_f32_e64 v35, v179, v161
	v_add_f32_e64 v34, v180, v34
	v_add_f32_e64 v35, v181, v35
	v_add_f32_e64 v34, v182, v34
	v_add_f32_e64 v35, v183, v35
	v_pk_add_f32 v[34:35], v[184:185], v[34:35]
	s_nop 0
	v_pk_add_f32 v[34:35], v[186:187], v[34:35]
	s_nop 0
	v_pk_add_f32 v[34:35], v[188:189], v[34:35]
	s_nop 0
	v_pk_add_f32 v[34:35], v[190:191], v[34:35]
	s_nop 0
	v_pk_add_f32 v[34:35], v[192:193], v[34:35]
	s_nop 0
	v_pk_add_f32 v[34:35], v[194:195], v[34:35]
	s_nop 0
	v_pk_add_f32 v[34:35], v[196:197], v[34:35]
	s_nop 0
	v_pk_add_f32 v[34:35], v[198:199], v[34:35]
	s_nop 0
	v_pk_add_f32 v[34:35], v[200:201], v[34:35]
	s_nop 0
	v_pk_add_f32 v[34:35], v[202:203], v[34:35]
	s_nop 0
	v_pk_add_f32 v[34:35], v[204:205], v[34:35]
	s_nop 0
	v_pk_add_f32 v[34:35], v[206:207], v[34:35]
	s_nop 0
	v_add_f32_e32 v51, v35, v33
	v_fmac_f32_e32 v51, v34, v32
	ds_read_b128 v[32:35], v213 offset:18432
	ds_read_b128 v[52:55], v213 offset:18464
	ds_read_b128 v[92:95], v213 offset:18496
	ds_read_b128 v[96:99], v213 offset:18528
	ds_read2_b32 v[74:75], v229 offset0:191 offset1:192
	ds_read2_b32 v[76:77], v229 offset0:193 offset1:194
	ds_read2_b32 v[78:79], v229 offset0:199 offset1:200
	ds_read2_b32 v[80:81], v229 offset0:201 offset1:202
	ds_read2_b32 v[82:83], v229 offset0:207 offset1:208
	ds_read2_b32 v[84:85], v229 offset0:209 offset1:210
	ds_read2_b32 v[86:87], v229 offset0:215 offset1:216
	ds_read2_b32 v[88:89], v229 offset0:217 offset1:218
	s_waitcnt lgkmcnt(11)
	v_mfma_f32_32x32x16_bf16 v[32:47], v[32:35], v[138:141], 0
	s_waitcnt lgkmcnt(10)
	v_mfma_f32_32x32x16_bf16 v[32:47], v[52:55], v[142:145], v[32:47]
	s_waitcnt lgkmcnt(9)
	v_mfma_f32_32x32x16_bf16 v[32:47], v[92:95], v[134:137], v[32:47]
	s_waitcnt lgkmcnt(8)
	v_mfma_f32_32x32x16_bf16 v[32:47], v[96:99], v[130:133], v[32:47]
	s_waitcnt lgkmcnt(0)
	s_nop 10
	v_add_f32_e32 v48, v32, v74
	v_add_f32_e32 v50, v33, v75
	v_max3_f32 v49, v231, v48, v50
	s_waitcnt lgkmcnt(0)
	v_add_f32_e32 v34, v34, v76
	v_add_f32_e32 v35, v35, v77
	v_max3_f32 v49, v49, v34, v35
	s_waitcnt lgkmcnt(0)
	v_add_f32_e32 v36, v36, v78
	v_add_f32_e32 v37, v37, v79
	v_max3_f32 v49, v49, v36, v37
	s_waitcnt lgkmcnt(0)
	v_add_f32_e32 v38, v38, v80
	v_add_f32_e32 v39, v39, v81
	v_max3_f32 v49, v49, v38, v39
	s_waitcnt lgkmcnt(0)
	v_add_f32_e32 v40, v40, v82
	v_add_f32_e32 v41, v41, v83
	v_max3_f32 v49, v49, v40, v41
	s_waitcnt lgkmcnt(0)
	v_add_f32_e32 v42, v42, v84
	v_add_f32_e32 v43, v43, v85
	v_max3_f32 v49, v49, v42, v43
	s_waitcnt lgkmcnt(0)
	v_add_f32_e32 v44, v44, v86
	v_add_f32_e32 v45, v45, v87
	v_max3_f32 v49, v49, v44, v45
	s_waitcnt lgkmcnt(0)
	v_add_f32_e32 v32, v46, v88
	v_add_f32_e32 v33, v47, v89
	v_max3_f32 v46, v49, v32, v33
	ds_bpermute_b32 v47, v171, v46
	s_waitcnt lgkmcnt(0)
	v_max_f32_e32 v47, v47, v47
	v_max_f32_e32 v49, v46, v47
	v_sub_f32_e32 v34, v34, v49
	v_mul_f32_e32 v34, 0x3fb8aa3b, v34
	v_exp_f32_e32 v186, v34
	v_sub_f32_e32 v34, v35, v49
	v_mul_f32_e32 v34, 0x3fb8aa3b, v34
	v_exp_f32_e32 v184, v34
	v_sub_f32_e32 v34, v36, v49
	v_mul_f32_e32 v34, 0x3fb8aa3b, v34
	v_exp_f32_e32 v182, v34
	v_sub_f32_e32 v34, v37, v49
	v_mul_f32_e32 v34, 0x3fb8aa3b, v34
	v_exp_f32_e32 v180, v34
	v_sub_f32_e32 v34, v38, v49
	v_mul_f32_e32 v34, 0x3fb8aa3b, v34
	v_exp_f32_e32 v178, v34
	v_sub_f32_e32 v34, v39, v49
	v_mul_f32_e32 v34, 0x3fb8aa3b, v34
	v_exp_f32_e32 v64, v34
	v_sub_f32_e32 v34, v40, v49
	v_mul_f32_e32 v34, 0x3fb8aa3b, v34
	v_exp_f32_e32 v62, v34
	v_sub_f32_e32 v34, v41, v49
	v_mul_f32_e32 v34, 0x3fb8aa3b, v34
	v_exp_f32_e32 v60, v34
	v_sub_f32_e32 v34, v42, v49
	v_sub_f32_e32 v47, v48, v49
	v_mul_f32_e32 v34, 0x3fb8aa3b, v34
	v_sub_f32_e32 v32, v32, v49
	v_mul_f32_e32 v47, 0x3fb8aa3b, v47
	v_exp_f32_e32 v58, v34
	v_sub_f32_e32 v34, v43, v49
	v_mul_f32_e32 v32, 0x3fb8aa3b, v32
	v_sub_f32_e32 v46, v231, v49
	v_exp_f32_e32 v53, v47
	v_sub_f32_e32 v47, v50, v49
	v_mul_f32_e32 v34, 0x3fb8aa3b, v34
	v_exp_f32_e32 v50, v32
	v_sub_f32_e32 v32, v33, v49
	v_mul_f32_e32 v46, 0x3fb8aa3b, v46
	v_mul_f32_e32 v47, 0x3fb8aa3b, v47
	v_exp_f32_e32 v56, v34
	v_sub_f32_e32 v34, v44, v49
	v_mul_f32_e32 v32, 0x3fb8aa3b, v32
	v_exp_f32_e32 v55, v47
	v_mul_f32_e32 v34, 0x3fb8aa3b, v34
	v_exp_f32_e32 v48, v32
	v_exp_f32_e32 v32, v46
	v_exp_f32_e32 v54, v34
	v_sub_f32_e32 v34, v45, v49
	ds_read2_b64 v[36:39], v153 offset0:32 offset1:34
	ds_read2_b64 v[40:43], v153 offset0:36 offset1:38
	ds_read2_b64 v[44:47], v230 offset0:96 offset1:98
	ds_read2_b64 v[190:193], v230 offset0:100 offset1:102
	v_mul_f32_e32 v34, 0x3fb8aa3b, v34
	v_exp_f32_e32 v52, v34
	v_mul_f32_e32 v188, v51, v32
	v_pk_mul_f32 v[14:15], v[14:15], v[32:33] op_sel_hi:[1,0]
	v_pk_mul_f32 v[12:13], v[12:13], v[32:33] op_sel_hi:[1,0]
	v_pk_mul_f32 v[10:11], v[10:11], v[32:33] op_sel_hi:[1,0]
	v_pk_mul_f32 v[8:9], v[8:9], v[32:33] op_sel_hi:[1,0]
	v_pk_mul_f32 v[6:7], v[6:7], v[32:33] op_sel_hi:[1,0]
	v_pk_mul_f32 v[4:5], v[4:5], v[32:33] op_sel_hi:[1,0]
	v_pk_mul_f32 v[2:3], v[2:3], v[32:33] op_sel_hi:[1,0]
	v_pk_mul_f32 v[0:1], v[0:1], v[32:33] op_sel_hi:[1,0]
	v_pk_mul_f32 v[30:31], v[30:31], v[32:33] op_sel_hi:[1,0]
	v_pk_mul_f32 v[28:29], v[28:29], v[32:33] op_sel_hi:[1,0]
	v_pk_mul_f32 v[26:27], v[26:27], v[32:33] op_sel_hi:[1,0]
	v_pk_mul_f32 v[24:25], v[24:25], v[32:33] op_sel_hi:[1,0]
	v_pk_mul_f32 v[22:23], v[22:23], v[32:33] op_sel_hi:[1,0]
	v_pk_mul_f32 v[20:21], v[20:21], v[32:33] op_sel_hi:[1,0]
	v_pk_mul_f32 v[18:19], v[18:19], v[32:33] op_sel_hi:[1,0]
	v_pk_mul_f32 v[16:17], v[16:17], v[32:33] op_sel_hi:[1,0]
	v_cvt_pk_bf16_f32 v32, v53, v55
	v_cvt_pk_bf16_f32 v33, v186, v184
	v_cvt_pk_bf16_f32 v34, v182, v180
	v_cvt_pk_bf16_f32 v35, v178, v64
	s_waitcnt lgkmcnt(3)
; #define LAS __attribute__((address_space(3)))
; __device__ __forceinline__ void attn_phase(CArgs a, int l, LAS unsigned char* lds, int tid, int lane, int wave, int G, int bx) {
;     ...
;                     for (int st = 0; st < 4; ++st) { const bf16x8 kf = *(const LAS bf16x8*)(Ks + (kvh * 192 + tt * 32 + ql) * 72 + st * 16 + hf * 8);
;                         sa = __builtin_amdgcn_mfma_f32_32x32x16_bf16(kf, qf[st], sa, 0, 0, 0); }
; #pragma unroll
;                     for (int i = 0; i < 16; ++i) sv[t3][i] = sa[i]; }
;                 float mn = mx;
; #pragma unroll
;                 for (int t3 = 0; t3 < 1; ++t3)
; #pragma unroll
;                     for (int i = 0; i < 16; ++i) { const int s = (ps + t3) * 32 + crow(i, hf); float v = sv[t3][i] + blh[s]; if (s < nmask) v = -1e30f; sv[t3][i] = v; mn = fmaxf(mn, v); }
;                 mn = fmaxf(mn, __shfl_xor(mn, 32));
;                 const float resc = __expf(mx - mn); mx = mn;
;                 float psum = 0.f;
; #pragma unroll
;                 for (int t3 = 0; t3 < 1; ++t3)
; #pragma unroll
;                     for (int i = 0; i < 16; ++i) { const float p = __expf(sv[t3][i] - mx); sv[t3][i] = p; psum += p; }
;                 sum = sum * resc + psum;
;                 o0 = o0 * resc; o1 = o1 * resc;
; #pragma unroll
;                 for (int t3 = 0; t3 < 1; ++t3)
; #pragma unroll
;                     for (int bb = 0; bb < 2; ++bb) { const int tt = ps + t3;
;                         u32x4 pw; pw.x = pk2(sv[t3][8 * bb], sv[t3][8 * bb + 1]); pw.y = pk2(sv[t3][8 * bb + 2], sv[t3][8 * bb + 3]); pw.z = pk2(sv[t3][8 * bb + 4], sv[t3][8 * bb + 5]); pw.w = pk2(sv[t3][8 * bb + 6], sv[t3][8 * bb + 7]);
;                         const bf16x8 pf = __builtin_bit_cast(bf16x8, pw);
;                         const LAS bf16_t* v0p = Vt + (kvh * 64 + ql) * 200 + tt * 32 + 16 * bb + 4 * hf;
;                         const LAS bf16_t* v1p = v0p + 32 * 200;
;                         u32x4 a0, a1; { const u32x2 lo = *(const LAS u32x2*)v0p, hi = *(const LAS u32x2*)(v0p + 8); a0.x = lo.x; a0.y = lo.y; a0.z = hi.x; a0.w = hi.y; }
;                         { const u32x2 lo = *(const LAS u32x2*)v1p, hi = *(const LAS u32x2*)(v1p + 8); a1.x = lo.x; a1.y = lo.y; a1.z = hi.x; a1.w = hi.y; }
;                         o0 = __builtin_amdgcn_mfma_f32_32x32x16_bf16(__builtin_bit_cast(bf16x8, a0), pf, o0, 0, 0, 0);
	s_nop 0
	v_mfma_f32_32x32x16_bf16 v[0:15], v[36:39], v[32:35], v[0:15]
	s_waitcnt lgkmcnt(1)
	v_mfma_f32_32x32x16_bf16 v[16:31], v[44:47], v[32:35], v[16:31]
	v_cvt_pk_bf16_f32 v32, v62, v60
	v_cvt_pk_bf16_f32 v33, v58, v56
	v_cvt_pk_bf16_f32 v34, v54, v52
	v_cvt_pk_bf16_f32 v35, v50, v48
	s_nop 1
	v_mfma_f32_32x32x16_bf16 v[0:15], v[40:43], v[32:35], v[0:15]
	s_waitcnt lgkmcnt(0)
	v_mfma_f32_32x32x16_bf16 v[16:31], v[190:193], v[32:35], v[16:31]
	v_add_f32_e32 v32, 0, v53
	v_add_f32_e32 v160, v55, v32
	ds_read_b128 v[32:35], v213 offset:23040
	ds_read_b128 v[190:193], v213 offset:23072
	ds_read_b128 v[92:95], v213 offset:23104
	ds_read_b128 v[96:99], v213 offset:23136
	ds_read2_b32 v[100:101], v229 offset0:223 offset1:224
	ds_read2_b32 v[102:103], v229 offset0:225 offset1:226
	ds_read2_b32 v[104:105], v229 offset0:231 offset1:232
	ds_read2_b32 v[106:107], v229 offset0:233 offset1:234
	ds_read2_b32 v[108:109], v229 offset0:239 offset1:240
	ds_read2_b32 v[110:111], v229 offset0:241 offset1:242
	ds_read2_b32 v[112:113], v229 offset0:247 offset1:248
	ds_read2_b32 v[90:91], v229 offset0:249 offset1:250
	s_waitcnt lgkmcnt(11)
	v_mfma_f32_32x32x16_bf16 v[32:47], v[32:35], v[138:141], 0
	s_waitcnt lgkmcnt(10)
	v_mfma_f32_32x32x16_bf16 v[32:47], v[190:193], v[142:145], v[32:47]
	s_waitcnt lgkmcnt(9)
	v_mfma_f32_32x32x16_bf16 v[32:47], v[92:95], v[134:137], v[32:47]
	s_waitcnt lgkmcnt(8)
	v_mfma_f32_32x32x16_bf16 v[32:47], v[96:99], v[130:133], v[32:47]
	s_waitcnt lgkmcnt(0)
	s_nop 10
	v_add_f32_e32 v51, v32, v100
	v_add_f32_e32 v53, v33, v101
	v_max3_f32 v55, v49, v51, v53
	s_waitcnt lgkmcnt(0)
	v_add_f32_e32 v34, v34, v102
	v_add_f32_e32 v35, v35, v103
	v_max3_f32 v55, v55, v34, v35
	s_waitcnt lgkmcnt(0)
	v_add_f32_e32 v36, v36, v104
	v_add_f32_e32 v37, v37, v105
	v_max3_f32 v55, v55, v36, v37
	s_waitcnt lgkmcnt(0)
	v_add_f32_e32 v38, v38, v106
	v_add_f32_e32 v39, v39, v107
	v_max3_f32 v55, v55, v38, v39
	s_waitcnt lgkmcnt(0)
	v_add_f32_e32 v40, v40, v108
	v_add_f32_e32 v41, v41, v109
	v_max3_f32 v55, v55, v40, v41
	s_waitcnt lgkmcnt(0)
	v_add_f32_e32 v42, v42, v110
	v_add_f32_e32 v43, v43, v111
	v_max3_f32 v55, v55, v42, v43
	s_waitcnt lgkmcnt(0)
	v_add_f32_e32 v44, v44, v112
	v_add_f32_e32 v45, v45, v113
	v_max3_f32 v55, v55, v44, v45
	s_waitcnt lgkmcnt(0)
	v_add_f32_e32 v32, v46, v90
	v_add_f32_e32 v33, v47, v91
	v_max3_f32 v46, v55, v32, v33
	ds_bpermute_b32 v47, v171, v46
	s_waitcnt lgkmcnt(0)
	v_max_f32_e32 v47, v47, v47
	v_max_f32_e32 v131, v46, v47
	v_sub_f32_e32 v34, v34, v131
	v_mul_f32_e32 v34, 0x3fb8aa3b, v34
	v_exp_f32_e32 v183, v34
	v_sub_f32_e32 v34, v35, v131
	v_mul_f32_e32 v34, 0x3fb8aa3b, v34
	v_exp_f32_e32 v181, v34
	v_sub_f32_e32 v34, v36, v131
	v_mul_f32_e32 v34, 0x3fb8aa3b, v34
	v_exp_f32_e32 v179, v34
	v_sub_f32_e32 v34, v37, v131
	v_mul_f32_e32 v34, 0x3fb8aa3b, v34
	v_exp_f32_e32 v65, v34
	v_sub_f32_e32 v34, v38, v131
	v_mul_f32_e32 v34, 0x3fb8aa3b, v34
	v_exp_f32_e32 v63, v34
	v_sub_f32_e32 v34, v39, v131
	v_mul_f32_e32 v34, 0x3fb8aa3b, v34
	v_exp_f32_e32 v61, v34
	v_sub_f32_e32 v34, v40, v131
	v_mul_f32_e32 v34, 0x3fb8aa3b, v34
	v_exp_f32_e32 v59, v34
	v_sub_f32_e32 v34, v41, v131
	v_mul_f32_e32 v34, 0x3fb8aa3b, v34
	v_sub_f32_e32 v46, v49, v131
	v_exp_f32_e32 v57, v34
	v_sub_f32_e32 v34, v42, v131
	v_mul_f32_e32 v46, 0x3fb8aa3b, v46
	v_sub_f32_e32 v47, v51, v131
	v_mul_f32_e32 v34, 0x3fb8aa3b, v34
	v_mul_f32_e32 v47, 0x3fb8aa3b, v47
	v_exp_f32_e32 v55, v34
	v_sub_f32_e32 v34, v43, v131
	v_exp_f32_e32 v130, v46
	v_exp_f32_e32 v187, v47
	v_sub_f32_e32 v47, v53, v131
	v_mul_f32_e32 v34, 0x3fb8aa3b, v34
	v_mul_f32_e32 v47, 0x3fb8aa3b, v47
	v_exp_f32_e32 v53, v34
	v_sub_f32_e32 v34, v44, v131
	v_exp_f32_e32 v185, v47
	v_mul_f32_e32 v34, 0x3fb8aa3b, v34
	v_sub_f32_e32 v32, v32, v131
	v_exp_f32_e32 v51, v34
	v_sub_f32_e32 v34, v45, v131
	v_mul_f32_e32 v32, 0x3fb8aa3b, v32
	v_pk_mul_f32 v[46:47], v[14:15], v[130:131] op_sel_hi:[1,0]
	v_pk_mul_f32 v[44:45], v[12:13], v[130:131] op_sel_hi:[1,0]
	v_pk_mul_f32 v[42:43], v[10:11], v[130:131] op_sel_hi:[1,0]
	v_pk_mul_f32 v[40:41], v[8:9], v[130:131] op_sel_hi:[1,0]
	v_pk_mul_f32 v[38:39], v[6:7], v[130:131] op_sel_hi:[1,0]
	v_pk_mul_f32 v[36:37], v[4:5], v[130:131] op_sel_hi:[1,0]
	v_pk_mul_f32 v[14:15], v[30:31], v[130:131] op_sel_hi:[1,0]
	v_pk_mul_f32 v[12:13], v[28:29], v[130:131] op_sel_hi:[1,0]
	v_pk_mul_f32 v[10:11], v[26:27], v[130:131] op_sel_hi:[1,0]
	v_pk_mul_f32 v[8:9], v[24:25], v[130:131] op_sel_hi:[1,0]
	v_pk_mul_f32 v[6:7], v[22:23], v[130:131] op_sel_hi:[1,0]
	v_pk_mul_f32 v[4:5], v[20:21], v[130:131] op_sel_hi:[1,0]
	ds_read2_b64 v[20:23], v153 offset0:40 offset1:42
	ds_read2_b64 v[24:27], v153 offset0:44 offset1:46
	ds_read2_b64 v[28:31], v230 offset0:104 offset1:106
	ds_read2_b64 v[132:135], v230 offset0:108 offset1:110
	v_exp_f32_e32 v189, v32
	v_sub_f32_e32 v32, v33, v131
	v_mul_f32_e32 v34, 0x3fb8aa3b, v34
	v_mul_f32_e32 v32, 0x3fb8aa3b, v32
	v_exp_f32_e32 v49, v34
	v_exp_f32_e32 v136, v32
	v_pk_mul_f32 v[34:35], v[2:3], v[130:131] op_sel_hi:[1,0]
	v_pk_mul_f32 v[32:33], v[0:1], v[130:131] op_sel_hi:[1,0]
	v_pk_mul_f32 v[2:3], v[18:19], v[130:131] op_sel_hi:[1,0]
	v_pk_mul_f32 v[0:1], v[16:17], v[130:131] op_sel_hi:[1,0]
	v_cvt_pk_bf16_f32 v16, v187, v185
	v_cvt_pk_bf16_f32 v17, v183, v181
	v_cvt_pk_bf16_f32 v18, v179, v65
	v_cvt_pk_bf16_f32 v19, v63, v61
	s_waitcnt lgkmcnt(3)
	s_nop 0
	v_mfma_f32_32x32x16_bf16 v[32:47], v[20:23], v[16:19], v[32:47]
	s_waitcnt lgkmcnt(1)
; __device__ __forceinline__ unsigned pk2(float lo, float hi) { const f32x2 v = {lo, hi}; return __builtin_bit_cast(unsigned, __builtin_convertvector(v, bf16x2_t)); }
; __device__ __forceinline__ void attn_phase(CArgs a, int l, LAS unsigned char* lds, int tid, int lane, int wave, int G, int bx) {
;     ...
;                         o0 = __builtin_amdgcn_mfma_f32_32x32x16_bf16(__builtin_bit_cast(bf16x8, a0), pf, o0, 0, 0, 0);
;                         o1 = __builtin_amdgcn_mfma_f32_32x32x16_bf16(__builtin_bit_cast(bf16x8, a1), pf, o1, 0, 0, 0);
;                     }
;             }
;             sum += __shfl_xor(sum, 32);
;             const float inv = 1.0f / (sum + __expf(sink - mx));
;             o0 = o0 * inv; o1 = o1 * inv;
; #pragma unroll
;             for (int i = 0; i < 16; ++i) ssq += o0[i] * o0[i] + o1[i] * o1[i];
; #pragma unroll
;             for (int i4 = 0; i4 < 4; ++i4) { const int col = 512 + h * 64 + 8 * i4 + 4 * hf;
;                 u32x2 w; w.x = pk2(o0[4 * i4], o0[4 * i4 + 1]); w.y = pk2(o0[4 * i4 + 2], o0[4 * i4 + 3]); *(u32x2*)(YC + (size_t)qtok * D + col) = w;
;                 u32x2 w2; w2.x = pk2(o1[4 * i4], o1[4 * i4 + 1]); w2.y = pk2(o1[4 * i4 + 2], o1[4 * i4 + 3]); *(u32x2*)(YC + (size_t)qtok * D + col + 32) = w2; }
;         }
;         ssq += __shfl_xor(ssq, 32);
;         if (lane < 32) RED[wave * 32 + ql] = ssq;
	v_mfma_f32_32x32x16_bf16 v[0:15], v[28:31], v[16:19], v[0:15]
	v_cvt_pk_bf16_f32 v16, v59, v57
	v_cvt_pk_bf16_f32 v17, v55, v53
	v_cvt_pk_bf16_f32 v18, v51, v49
	v_cvt_pk_bf16_f32 v19, v189, v136
	s_nop 1
	v_mfma_f32_32x32x16_bf16 v[32:47], v[24:27], v[16:19], v[32:47]
	s_waitcnt lgkmcnt(0)
	v_mfma_f32_32x32x16_bf16 v[0:15], v[132:135], v[16:19], v[0:15]
	v_add_f32_e64 v16, v186, v160
	v_add_f32_e64 v17, v187, v161
	v_add_f32_e64 v16, v184, v16
	v_add_f32_e64 v17, v185, v17
	v_add_f32_e64 v16, v182, v16
	v_add_f32_e64 v17, v183, v17
	v_pk_add_f32 v[16:17], v[180:181], v[16:17]
	s_nop 0
	v_pk_add_f32 v[16:17], v[178:179], v[16:17]
	s_nop 0
	v_pk_add_f32 v[16:17], v[64:65], v[16:17]
	s_nop 0
	v_pk_add_f32 v[16:17], v[62:63], v[16:17]
	s_nop 0
	v_pk_add_f32 v[16:17], v[60:61], v[16:17]
	s_nop 0
	v_pk_add_f32 v[16:17], v[58:59], v[16:17]
	s_nop 0
	v_pk_add_f32 v[16:17], v[56:57], v[16:17]
	s_nop 0
	v_pk_add_f32 v[16:17], v[54:55], v[16:17]
	s_nop 0
	v_pk_add_f32 v[16:17], v[52:53], v[16:17]
	s_nop 0
	v_pk_add_f32 v[16:17], v[50:51], v[16:17]
	s_nop 0
	v_pk_add_f32 v[16:17], v[48:49], v[16:17]
	s_nop 0
	v_pk_add_f32 v[16:17], v[188:189], v[16:17]
	s_nop 0
	v_add_f32_e32 v17, v17, v136
	v_fmac_f32_e32 v17, v16, v130
	ds_bpermute_b32 v16, v171, v17
	s_waitcnt lgkmcnt(0)
	v_add_f32_e32 v16, v17, v16
	v_sub_f32_e32 v17, v228, v131
	v_mul_f32_e32 v17, 0x3fb8aa3b, v17
	v_exp_f32_e32 v17, v17
	s_nop 0
	v_add_f32_e32 v16, v17, v16
	v_div_scale_f32 v17, s[90:91], v16, v16, 1.0
	v_rcp_f32_e32 v18, v17
	s_mov_b32 s90, 1
	v_fma_f32 v19, -v17, v18, 1.0
	v_fmac_f32_e32 v18, v19, v18
	v_div_scale_f32 v19, vcc, 1.0, v16, 1.0
	v_mul_f32_e32 v20, v19, v18
	v_fma_f32 v21, -v17, v20, v19
	v_fmac_f32_e32 v20, v21, v18
	v_fma_f32 v17, -v17, v20, v19
	v_div_fmas_f32 v17, v17, v18, v20
	v_div_fixup_f32 v24, v17, v16, 1.0
	v_pk_mul_f32 v[16:17], v[44:45], v[24:25] op_sel_hi:[1,0]
	v_or_b32_e32 v44, 0x200, v148
	v_pk_mul_f32 v[26:27], v[36:37], v[24:25] op_sel_hi:[1,0]
	v_pk_mul_f32 v[28:29], v[38:39], v[24:25] op_sel_hi:[1,0]
	v_pk_mul_f32 v[36:37], v[2:3], v[24:25] op_sel_hi:[1,0]
	v_pk_mul_f32 v[38:39], v[0:1], v[24:25] op_sel_hi:[1,0]
	v_lshl_add_u32 v44, s2, 6, v44
	v_pk_mul_f32 v[20:21], v[40:41], v[24:25] op_sel_hi:[1,0]
	v_pk_mul_f32 v[22:23], v[42:43], v[24:25] op_sel_hi:[1,0]
	v_pk_mul_f32 v[18:19], v[46:47], v[24:25] op_sel_hi:[1,0]
	v_pk_mul_f32 v[40:41], v[34:35], v[24:25] op_sel_hi:[1,0]
	v_pk_mul_f32 v[42:43], v[32:33], v[24:25] op_sel_hi:[1,0]
	v_pk_mul_f32 v[10:11], v[10:11], v[24:25] op_sel_hi:[1,0]
	v_pk_mul_f32 v[8:9], v[8:9], v[24:25] op_sel_hi:[1,0]
	v_mul_f32_e32 v46, v38, v38
	v_mul_f32_e32 v47, v39, v39
	v_mul_f32_e32 v48, v36, v36
	v_mul_f32_e32 v49, v37, v37
	v_ashrrev_i32_e32 v45, 31, v44
	v_pk_mul_f32 v[32:33], v[6:7], v[24:25] op_sel_hi:[1,0]
	v_fmac_f32_e32 v46, v42, v42
	v_fmac_f32_e32 v47, v43, v43
	v_fmac_f32_e32 v48, v40, v40
	v_fmac_f32_e32 v49, v41, v41
	v_pk_mul_f32 v[6:7], v[8:9], v[8:9]
	v_cvt_pk_bf16_f32 v42, v42, v43
	v_cvt_pk_bf16_f32 v43, v40, v41
	v_lshl_add_u64 v[40:41], v[44:45], 1, v[176:177]
	v_cvt_pk_bf16_f32 v8, v8, v9
	v_cvt_pk_bf16_f32 v9, v10, v11
	v_pk_mul_f32 v[14:15], v[14:15], v[24:25] op_sel_hi:[1,0]
	v_pk_mul_f32 v[12:13], v[12:13], v[24:25] op_sel_hi:[1,0]
	global_store_dwordx2 v[40:41], v[8:9], off offset:96
	v_cvt_pk_bf16_f32 v8, v16, v17
	v_cvt_pk_bf16_f32 v9, v18, v19
	global_store_dwordx2 v[40:41], v[8:9], off offset:48
	v_cvt_pk_bf16_f32 v8, v12, v13
	v_cvt_pk_bf16_f32 v9, v14, v15
	global_store_dwordx2 v[40:41], v[8:9], off offset:112
	v_add_f32_e32 v8, v226, v46
	v_pk_mul_f32 v[34:35], v[4:5], v[24:25] op_sel_hi:[1,0]
	v_add_f32_e32 v8, v47, v8
	v_pk_mul_f32 v[30:31], v[34:35], v[34:35]
	v_add_f32_e32 v8, v48, v8
	v_pk_fma_f32 v[30:31], v[26:27], v[26:27], v[30:31]
	v_add_f32_e32 v8, v49, v8
	v_pk_mul_f32 v[24:25], v[32:33], v[32:33]
	v_add_f32_e32 v8, v30, v8
	v_pk_fma_f32 v[24:25], v[28:29], v[28:29], v[24:25]
	v_add_f32_e32 v8, v31, v8
	v_add_f32_e32 v8, v24, v8
	v_pk_fma_f32 v[6:7], v[20:21], v[20:21], v[6:7]
	v_add_f32_e32 v8, v25, v8
	v_pk_mul_f32 v[4:5], v[10:11], v[10:11]
	v_add_f32_e32 v6, v6, v8
	v_pk_fma_f32 v[4:5], v[22:23], v[22:23], v[4:5]
	v_add_f32_e32 v6, v7, v6
	v_pk_mul_f32 v[2:3], v[12:13], v[12:13]
	v_add_f32_e32 v4, v4, v6
	v_pk_fma_f32 v[2:3], v[16:17], v[16:17], v[2:3]
	v_add_f32_e32 v4, v5, v4
	v_pk_mul_f32 v[0:1], v[14:15], v[14:15]
	v_add_f32_e32 v2, v2, v4
	v_pk_fma_f32 v[0:1], v[18:19], v[18:19], v[0:1]
	v_add_f32_e32 v2, v3, v2
	v_cvt_pk_bf16_f32 v26, v26, v27
	v_cvt_pk_bf16_f32 v27, v28, v29
	v_add_f32_e32 v0, v0, v2
	v_cvt_pk_bf16_f32 v38, v38, v39
	v_cvt_pk_bf16_f32 v39, v36, v37
	global_store_dwordx2 v[40:41], v[26:27], off offset:16
	v_cvt_pk_bf16_f32 v26, v34, v35
	v_cvt_pk_bf16_f32 v27, v32, v33
	v_cvt_pk_bf16_f32 v20, v20, v21
	v_cvt_pk_bf16_f32 v21, v22, v23
	v_add_f32_e32 v226, v1, v0
	s_mov_b64 s[2:3], 0
	s_and_b64 vcc, exec, s[88:89]
	global_store_dwordx2 v[40:41], v[42:43], off
	global_store_dwordx2 v[40:41], v[38:39], off offset:64
	global_store_dwordx2 v[40:41], v[26:27], off offset:80
	global_store_dwordx2 v[40:41], v[20:21], off offset:32
	s_cbranch_vccz .LBB0_357
	ds_bpermute_b32 v0, v171, v226
	s_mov_b64 s[0:1], exec
	v_readlane_b32 s2, v255, 30
	v_readlane_b32 s3, v255, 31
	s_and_b64 s[2:3], s[0:1], s[2:3]
	s_mov_b32 s81, 0x8000
	s_mov_b32 s84, 0xc000
	s_movk_i32 s85, 0xa00
	s_movk_i32 s86, 0x1000
	s_movk_i32 s87, 0x1ff
	s_movk_i32 s88, 0xdff
	s_movk_i32 s89, 0x7f
	s_mov_b64 exec, s[2:3]
	s_cbranch_execz .LBB0_276
	s_waitcnt lgkmcnt(0)
	v_add_f32_e32 v0, v226, v0
	ds_write_b32 v225, v0
	s_branch .LBB0_276
